# v9: nt cache policy on the once-read f32 master-weight and input streams (prologue and MoE weight prep loops)
# speedup vs baseline: 1.0138x; 1.0138x over previous
.LBB0_9:
	s_mul_hi_i32 s0, s47, 0x4ec4ec4f
	s_lshr_b32 s1, s0, 31
	s_ashr_i32 s0, s0, 5
	s_add_i32 s0, s0, s1
	s_lshl_b32 s42, s0, 6
	s_mulk_i32 s0, 0xf300
	s_add_i32 s40, s3, s0
	v_add_u32_e32 v2, s40, v42
	s_ashr_i32 s41, s40, 31
	v_cmp_gt_i32_e32 vcc, s5, v2
	v_or_b32_e32 v47, s42, v43
	v_lshl_add_u64 v[40:41], s[40:41], 2, v[36:37]
	v_mov_b32_e32 v2, 0
	v_mov_b32_e32 v3, 0
	v_mov_b32_e32 v4, 0
	v_mov_b32_e32 v5, 0
	s_and_saveexec_b64 s[44:45], vcc
	s_cbranch_execz .LBB0_11
	v_mad_i64_i32 v[2:3], s[0:1], v47, s46, v[40:41]
	global_load_dwordx4 v[2:5], v[2:3], off nt
.LBB0_11:
	s_or_b64 exec, exec, s[44:45]
	v_mov_b32_e32 v6, 0
	v_mov_b32_e32 v10, 0
	v_mov_b32_e32 v11, 0
	v_mov_b32_e32 v12, 0
	v_mov_b32_e32 v13, 0
	s_and_saveexec_b64 s[44:45], vcc
	s_cbranch_execz .LBB0_13
	v_or_b32_e32 v7, 8, v47
	v_mad_i64_i32 v[8:9], s[0:1], v7, s46, v[40:41]
	global_load_dwordx4 v[10:13], v[8:9], off nt
.LBB0_13:
	s_or_b64 exec, exec, s[44:45]
	v_mov_b32_e32 v7, 0
	v_mov_b32_e32 v8, 0
	v_mov_b32_e32 v9, 0
	s_and_saveexec_b64 s[44:45], vcc
	s_cbranch_execz .LBB0_15
	v_or_b32_e32 v6, 16, v47
	v_mad_i64_i32 v[6:7], s[0:1], v6, s46, v[40:41]
	global_load_dwordx4 v[6:9], v[6:7], off nt
.LBB0_15:
	s_or_b64 exec, exec, s[44:45]
	v_mov_b32_e32 v14, 0
	v_mov_b32_e32 v18, 0
	v_mov_b32_e32 v19, 0
	v_mov_b32_e32 v20, 0
	v_mov_b32_e32 v21, 0
	s_and_saveexec_b64 s[44:45], vcc
	s_cbranch_execz .LBB0_17
	v_or_b32_e32 v15, 24, v47
	v_mad_i64_i32 v[16:17], s[0:1], v15, s46, v[40:41]
	global_load_dwordx4 v[18:21], v[16:17], off nt
.LBB0_17:
	s_or_b64 exec, exec, s[44:45]
	v_mov_b32_e32 v15, 0
	v_mov_b32_e32 v16, 0
	v_mov_b32_e32 v17, 0
	s_and_saveexec_b64 s[44:45], vcc
	s_cbranch_execz .LBB0_19
	v_or_b32_e32 v14, 32, v47
	v_mad_i64_i32 v[14:15], s[0:1], v14, s46, v[40:41]
	global_load_dwordx4 v[14:17], v[14:15], off nt
.LBB0_19:
	s_or_b64 exec, exec, s[44:45]
	v_mov_b32_e32 v22, 0
	v_mov_b32_e32 v26, 0
	v_mov_b32_e32 v27, 0
	v_mov_b32_e32 v28, 0
	v_mov_b32_e32 v29, 0
	s_and_saveexec_b64 s[44:45], vcc
	s_cbranch_execz .LBB0_21
	v_or_b32_e32 v23, 40, v47
	v_mad_i64_i32 v[24:25], s[0:1], v23, s46, v[40:41]
	global_load_dwordx4 v[26:29], v[24:25], off nt
.LBB0_21:
	s_or_b64 exec, exec, s[44:45]
	v_mov_b32_e32 v23, 0
	v_mov_b32_e32 v24, 0
	v_mov_b32_e32 v25, 0
	s_and_saveexec_b64 s[44:45], vcc
	s_cbranch_execz .LBB0_23
	v_or_b32_e32 v22, 48, v47
	v_mad_i64_i32 v[22:23], s[0:1], v22, s46, v[40:41]
	global_load_dwordx4 v[22:25], v[22:23], off nt
.LBB0_23:
	s_or_b64 exec, exec, s[44:45]
	v_mov_b32_e32 v30, 0
	v_mov_b32_e32 v31, 0
	v_mov_b32_e32 v32, 0
	v_mov_b32_e32 v33, 0
	s_and_saveexec_b64 s[44:45], vcc
	s_cbranch_execz .LBB0_8
	v_or_b32_e32 v30, 56, v47
	v_mad_i64_i32 v[30:31], s[0:1], v30, s46, v[40:41]
	global_load_dwordx4 v[30:33], v[30:31], off nt
	s_branch .LBB0_8

.LBB0_28:
	s_ashr_i32 s0, s46, 31
	s_lshr_b32 s0, s0, 27
	s_add_i32 s0, s46, s0
	s_ashr_i32 s0, s0, 5
	s_lshl_b32 s1, s0, 10
	s_sub_i32 s44, s3, s1
	s_lshl_b32 s28, s0, 6
	v_add_u32_e32 v2, s44, v45
	s_ashr_i32 s45, s44, 31
	v_cmp_gt_i32_e32 vcc, s5, v2
	v_or_b32_e32 v42, s28, v46
	v_lshl_add_u64 v[40:41], s[44:45], 2, v[36:37]
	v_mov_b32_e32 v2, 0
	v_mov_b32_e32 v3, 0
	v_mov_b32_e32 v4, 0
	v_mov_b32_e32 v5, 0
	s_and_saveexec_b64 s[44:45], vcc
	s_cbranch_execz .LBB0_30
	v_ashrrev_i32_e32 v43, 31, v42
	v_lshlrev_b64 v[2:3], 12, v[42:43]
	v_lshl_add_u64 v[2:3], v[40:41], 0, v[2:3]
	global_load_dwordx4 v[2:5], v[2:3], off nt
.LBB0_30:
	s_or_b64 exec, exec, s[44:45]
	v_mov_b32_e32 v6, 0
	v_mov_b32_e32 v10, 0
	v_mov_b32_e32 v11, 0
	v_mov_b32_e32 v12, 0
	v_mov_b32_e32 v13, 0
	s_and_saveexec_b64 s[44:45], vcc
	s_cbranch_execz .LBB0_32
	v_or_b32_e32 v8, 8, v42
	v_ashrrev_i32_e32 v9, 31, v8
	v_lshlrev_b64 v[8:9], 12, v[8:9]
	v_lshl_add_u64 v[8:9], v[40:41], 0, v[8:9]
	global_load_dwordx4 v[10:13], v[8:9], off nt
.LBB0_32:
	s_or_b64 exec, exec, s[44:45]
	v_mov_b32_e32 v7, 0
	v_mov_b32_e32 v8, 0
	v_mov_b32_e32 v9, 0
	s_and_saveexec_b64 s[44:45], vcc
	s_cbranch_execz .LBB0_34
	v_or_b32_e32 v6, 16, v42
	v_ashrrev_i32_e32 v7, 31, v6
	v_lshlrev_b64 v[6:7], 12, v[6:7]
	v_lshl_add_u64 v[6:7], v[40:41], 0, v[6:7]
	global_load_dwordx4 v[6:9], v[6:7], off nt
.LBB0_34:
	s_or_b64 exec, exec, s[44:45]
	v_mov_b32_e32 v14, 0
	v_mov_b32_e32 v18, 0
	v_mov_b32_e32 v19, 0
	v_mov_b32_e32 v20, 0
	v_mov_b32_e32 v21, 0
	s_and_saveexec_b64 s[44:45], vcc
	s_cbranch_execz .LBB0_36
	v_or_b32_e32 v16, 24, v42
	v_ashrrev_i32_e32 v17, 31, v16
	v_lshlrev_b64 v[16:17], 12, v[16:17]
	v_lshl_add_u64 v[16:17], v[40:41], 0, v[16:17]
	global_load_dwordx4 v[18:21], v[16:17], off nt
.LBB0_36:
	s_or_b64 exec, exec, s[44:45]
	v_mov_b32_e32 v15, 0
	v_mov_b32_e32 v16, 0
	v_mov_b32_e32 v17, 0
	s_and_saveexec_b64 s[44:45], vcc
	s_cbranch_execz .LBB0_38
	v_or_b32_e32 v14, 32, v42
	v_ashrrev_i32_e32 v15, 31, v14
	v_lshlrev_b64 v[14:15], 12, v[14:15]
	v_lshl_add_u64 v[14:15], v[40:41], 0, v[14:15]
	global_load_dwordx4 v[14:17], v[14:15], off nt
.LBB0_38:
	s_or_b64 exec, exec, s[44:45]
	v_mov_b32_e32 v22, 0
	v_mov_b32_e32 v26, 0
	v_mov_b32_e32 v27, 0
	v_mov_b32_e32 v28, 0
	v_mov_b32_e32 v29, 0
	s_and_saveexec_b64 s[44:45], vcc
	s_cbranch_execz .LBB0_40
	v_or_b32_e32 v24, 40, v42
	v_ashrrev_i32_e32 v25, 31, v24
	v_lshlrev_b64 v[24:25], 12, v[24:25]
	v_lshl_add_u64 v[24:25], v[40:41], 0, v[24:25]
	global_load_dwordx4 v[26:29], v[24:25], off nt
.LBB0_40:
	s_or_b64 exec, exec, s[44:45]
	v_mov_b32_e32 v23, 0
	v_mov_b32_e32 v24, 0
	v_mov_b32_e32 v25, 0
	s_and_saveexec_b64 s[44:45], vcc
	s_cbranch_execz .LBB0_42
	v_or_b32_e32 v22, 48, v42
	v_ashrrev_i32_e32 v23, 31, v22
	v_lshlrev_b64 v[22:23], 12, v[22:23]
	v_lshl_add_u64 v[22:23], v[40:41], 0, v[22:23]
	global_load_dwordx4 v[22:25], v[22:23], off nt
.LBB0_42:
	s_or_b64 exec, exec, s[44:45]
	v_mov_b32_e32 v30, 0
	v_mov_b32_e32 v31, 0
	v_mov_b32_e32 v32, 0
	v_mov_b32_e32 v33, 0
	s_and_saveexec_b64 s[44:45], vcc
	s_cbranch_execz .LBB0_27
	v_or_b32_e32 v30, 56, v42
	v_ashrrev_i32_e32 v31, 31, v30
	v_lshlrev_b64 v[30:31], 12, v[30:31]
	v_lshl_add_u64 v[30:31], v[40:41], 0, v[30:31]
	global_load_dwordx4 v[30:33], v[30:31], off nt
	s_branch .LBB0_27

.LBB0_47:
	s_mul_hi_i32 s0, s45, 0x4ec4ec4f
	s_lshr_b32 s1, s0, 31
	s_ashr_i32 s0, s0, 5
	s_add_i32 s0, s0, s1
	s_lshl_b32 s28, s0, 6
	s_mulk_i32 s0, 0xf300
	s_add_i32 s6, s3, s0
	v_add_u32_e32 v2, s6, v42
	s_ashr_i32 s7, s6, 31
	v_cmp_gt_i32_e32 vcc, s5, v2
	v_or_b32_e32 v47, s28, v43
	v_lshl_add_u64 v[40:41], s[6:7], 2, v[36:37]
	v_mov_b32_e32 v2, 0
	v_mov_b32_e32 v3, 0
	v_mov_b32_e32 v4, 0
	v_mov_b32_e32 v5, 0
	s_and_saveexec_b64 s[30:31], vcc
	s_cbranch_execz .LBB0_49
	v_mad_i64_i32 v[2:3], s[0:1], v47, s44, v[40:41]
	global_load_dwordx4 v[2:5], v[2:3], off nt
.LBB0_49:
	s_or_b64 exec, exec, s[30:31]
	v_mov_b32_e32 v6, 0
	v_mov_b32_e32 v10, 0
	v_mov_b32_e32 v11, 0
	v_mov_b32_e32 v12, 0
	v_mov_b32_e32 v13, 0
	s_and_saveexec_b64 s[30:31], vcc
	s_cbranch_execz .LBB0_51
	v_or_b32_e32 v7, 8, v47
	v_mad_i64_i32 v[8:9], s[0:1], v7, s44, v[40:41]
	global_load_dwordx4 v[10:13], v[8:9], off nt
.LBB0_51:
	s_or_b64 exec, exec, s[30:31]
	v_mov_b32_e32 v7, 0
	v_mov_b32_e32 v8, 0
	v_mov_b32_e32 v9, 0
	s_and_saveexec_b64 s[30:31], vcc
	s_cbranch_execz .LBB0_53
	v_or_b32_e32 v6, 16, v47
	v_mad_i64_i32 v[6:7], s[0:1], v6, s44, v[40:41]
	global_load_dwordx4 v[6:9], v[6:7], off nt
.LBB0_53:
	s_or_b64 exec, exec, s[30:31]
	v_mov_b32_e32 v14, 0
	v_mov_b32_e32 v18, 0
	v_mov_b32_e32 v19, 0
	v_mov_b32_e32 v20, 0
	v_mov_b32_e32 v21, 0
	s_and_saveexec_b64 s[30:31], vcc
	s_cbranch_execz .LBB0_55
	v_or_b32_e32 v15, 24, v47
	v_mad_i64_i32 v[16:17], s[0:1], v15, s44, v[40:41]
	global_load_dwordx4 v[18:21], v[16:17], off nt
.LBB0_55:
	s_or_b64 exec, exec, s[30:31]
	v_mov_b32_e32 v15, 0
	v_mov_b32_e32 v16, 0
	v_mov_b32_e32 v17, 0
	s_and_saveexec_b64 s[30:31], vcc
	s_cbranch_execz .LBB0_57
	v_or_b32_e32 v14, 32, v47
	v_mad_i64_i32 v[14:15], s[0:1], v14, s44, v[40:41]
	global_load_dwordx4 v[14:17], v[14:15], off nt
.LBB0_57:
	s_or_b64 exec, exec, s[30:31]
	v_mov_b32_e32 v22, 0
	v_mov_b32_e32 v26, 0
	v_mov_b32_e32 v27, 0
	v_mov_b32_e32 v28, 0
	v_mov_b32_e32 v29, 0
	s_and_saveexec_b64 s[30:31], vcc
	s_cbranch_execz .LBB0_59
	v_or_b32_e32 v23, 40, v47
	v_mad_i64_i32 v[24:25], s[0:1], v23, s44, v[40:41]
	global_load_dwordx4 v[26:29], v[24:25], off nt
.LBB0_59:
	s_or_b64 exec, exec, s[30:31]
	v_mov_b32_e32 v23, 0
	v_mov_b32_e32 v24, 0
	v_mov_b32_e32 v25, 0
	s_and_saveexec_b64 s[30:31], vcc
	s_cbranch_execz .LBB0_61
	v_or_b32_e32 v22, 48, v47
	v_mad_i64_i32 v[22:23], s[0:1], v22, s44, v[40:41]
	global_load_dwordx4 v[22:25], v[22:23], off nt
.LBB0_61:
	s_or_b64 exec, exec, s[30:31]
	v_mov_b32_e32 v30, 0
	v_mov_b32_e32 v31, 0
	v_mov_b32_e32 v32, 0
	v_mov_b32_e32 v33, 0
	s_and_saveexec_b64 s[30:31], vcc
	s_cbranch_execz .LBB0_46
	v_or_b32_e32 v30, 56, v47
	v_mad_i64_i32 v[30:31], s[0:1], v30, s44, v[40:41]
	global_load_dwordx4 v[30:33], v[30:31], off nt
	s_branch .LBB0_46

.LBB0_66:
	s_ashr_i32 s0, s30, 31
	s_lshr_b32 s0, s0, 27
	s_add_i32 s0, s30, s0
	s_ashr_i32 s0, s0, 5
	s_lshl_b32 s1, s0, 10
	s_sub_i32 s28, s3, s1
	s_lshl_b32 s24, s0, 6
	v_add_u32_e32 v2, s28, v45
	s_ashr_i32 s29, s28, 31
	v_cmp_gt_i32_e32 vcc, s5, v2
	v_or_b32_e32 v42, s24, v46
	v_lshl_add_u64 v[40:41], s[28:29], 2, v[36:37]
	v_mov_b32_e32 v2, 0
	v_mov_b32_e32 v3, 0
	v_mov_b32_e32 v4, 0
	v_mov_b32_e32 v5, 0
	s_and_saveexec_b64 s[28:29], vcc
	s_cbranch_execz .LBB0_68
	v_ashrrev_i32_e32 v43, 31, v42
	v_lshlrev_b64 v[2:3], 12, v[42:43]
	v_lshl_add_u64 v[2:3], v[40:41], 0, v[2:3]
	global_load_dwordx4 v[2:5], v[2:3], off nt
.LBB0_68:
	s_or_b64 exec, exec, s[28:29]
	v_mov_b32_e32 v6, 0
	v_mov_b32_e32 v10, 0
	v_mov_b32_e32 v11, 0
	v_mov_b32_e32 v12, 0
	v_mov_b32_e32 v13, 0
	s_and_saveexec_b64 s[28:29], vcc
	s_cbranch_execz .LBB0_70
	v_or_b32_e32 v8, 8, v42
	v_ashrrev_i32_e32 v9, 31, v8
	v_lshlrev_b64 v[8:9], 12, v[8:9]
	v_lshl_add_u64 v[8:9], v[40:41], 0, v[8:9]
	global_load_dwordx4 v[10:13], v[8:9], off nt
.LBB0_70:
	s_or_b64 exec, exec, s[28:29]
	v_mov_b32_e32 v7, 0
	v_mov_b32_e32 v8, 0
	v_mov_b32_e32 v9, 0
	s_and_saveexec_b64 s[28:29], vcc
	s_cbranch_execz .LBB0_72
	v_or_b32_e32 v6, 16, v42
	v_ashrrev_i32_e32 v7, 31, v6
	v_lshlrev_b64 v[6:7], 12, v[6:7]
	v_lshl_add_u64 v[6:7], v[40:41], 0, v[6:7]
	global_load_dwordx4 v[6:9], v[6:7], off nt
.LBB0_72:
	s_or_b64 exec, exec, s[28:29]
	v_mov_b32_e32 v14, 0
	v_mov_b32_e32 v18, 0
	v_mov_b32_e32 v19, 0
	v_mov_b32_e32 v20, 0
	v_mov_b32_e32 v21, 0
	s_and_saveexec_b64 s[28:29], vcc
	s_cbranch_execz .LBB0_74
	v_or_b32_e32 v16, 24, v42
	v_ashrrev_i32_e32 v17, 31, v16
	v_lshlrev_b64 v[16:17], 12, v[16:17]
	v_lshl_add_u64 v[16:17], v[40:41], 0, v[16:17]
	global_load_dwordx4 v[18:21], v[16:17], off nt
.LBB0_74:
	s_or_b64 exec, exec, s[28:29]
	v_mov_b32_e32 v15, 0
	v_mov_b32_e32 v16, 0
	v_mov_b32_e32 v17, 0
	s_and_saveexec_b64 s[28:29], vcc
	s_cbranch_execz .LBB0_76
	v_or_b32_e32 v14, 32, v42
	v_ashrrev_i32_e32 v15, 31, v14
	v_lshlrev_b64 v[14:15], 12, v[14:15]
	v_lshl_add_u64 v[14:15], v[40:41], 0, v[14:15]
	global_load_dwordx4 v[14:17], v[14:15], off nt
.LBB0_76:
	s_or_b64 exec, exec, s[28:29]
	v_mov_b32_e32 v22, 0
	v_mov_b32_e32 v26, 0
	v_mov_b32_e32 v27, 0
	v_mov_b32_e32 v28, 0
	v_mov_b32_e32 v29, 0
	s_and_saveexec_b64 s[28:29], vcc
	s_cbranch_execz .LBB0_78
	v_or_b32_e32 v24, 40, v42
	v_ashrrev_i32_e32 v25, 31, v24
	v_lshlrev_b64 v[24:25], 12, v[24:25]
	v_lshl_add_u64 v[24:25], v[40:41], 0, v[24:25]
	global_load_dwordx4 v[26:29], v[24:25], off nt
.LBB0_78:
	s_or_b64 exec, exec, s[28:29]
	v_mov_b32_e32 v23, 0
	v_mov_b32_e32 v24, 0
	v_mov_b32_e32 v25, 0
	s_and_saveexec_b64 s[28:29], vcc
	s_cbranch_execz .LBB0_80
	v_or_b32_e32 v22, 48, v42
	v_ashrrev_i32_e32 v23, 31, v22
	v_lshlrev_b64 v[22:23], 12, v[22:23]
	v_lshl_add_u64 v[22:23], v[40:41], 0, v[22:23]
	global_load_dwordx4 v[22:25], v[22:23], off nt
.LBB0_80:
	s_or_b64 exec, exec, s[28:29]
	v_mov_b32_e32 v30, 0
	v_mov_b32_e32 v31, 0
	v_mov_b32_e32 v32, 0
	v_mov_b32_e32 v33, 0
	s_and_saveexec_b64 s[28:29], vcc
	s_cbranch_execz .LBB0_65
	v_or_b32_e32 v30, 56, v42
	v_ashrrev_i32_e32 v31, 31, v30
	v_lshlrev_b64 v[30:31], 12, v[30:31]
	v_lshl_add_u64 v[30:31], v[40:41], 0, v[30:31]
	global_load_dwordx4 v[30:33], v[30:31], off nt
	s_branch .LBB0_65

.LBB0_85:
	s_ashr_i32 s0, s28, 31
	s_lshr_b32 s0, s0, 26
	s_add_i32 s0, s28, s0
	s_and_b32 s24, s0, 0xffffffc0
	s_lshl_b32 s0, s0, 5
	s_and_b32 s1, s0, 0xfffff800
	s_sub_i32 s26, s3, s1
	v_add_u32_e32 v2, s26, v45
	s_ashr_i32 s27, s26, 31
	v_cmp_gt_i32_e32 vcc, s5, v2
	v_or_b32_e32 v42, s24, v46
	v_lshl_add_u64 v[40:41], s[26:27], 2, v[36:37]
	v_mov_b32_e32 v2, 0
	v_mov_b32_e32 v3, 0
	v_mov_b32_e32 v4, 0
	v_mov_b32_e32 v5, 0
	s_and_saveexec_b64 s[26:27], vcc
	s_cbranch_execz .LBB0_87
	v_ashrrev_i32_e32 v43, 31, v42
	v_lshlrev_b64 v[2:3], 13, v[42:43]
	v_lshl_add_u64 v[2:3], v[40:41], 0, v[2:3]
	global_load_dwordx4 v[2:5], v[2:3], off nt
.LBB0_87:
	s_or_b64 exec, exec, s[26:27]
	v_mov_b32_e32 v6, 0
	v_mov_b32_e32 v10, 0
	v_mov_b32_e32 v11, 0
	v_mov_b32_e32 v12, 0
	v_mov_b32_e32 v13, 0
	s_and_saveexec_b64 s[26:27], vcc
	s_cbranch_execz .LBB0_89
	v_or_b32_e32 v8, 8, v42
	v_ashrrev_i32_e32 v9, 31, v8
	v_lshlrev_b64 v[8:9], 13, v[8:9]
	v_lshl_add_u64 v[8:9], v[40:41], 0, v[8:9]
	global_load_dwordx4 v[10:13], v[8:9], off nt
.LBB0_89:
	s_or_b64 exec, exec, s[26:27]
	v_mov_b32_e32 v7, 0
	v_mov_b32_e32 v8, 0
	v_mov_b32_e32 v9, 0
	s_and_saveexec_b64 s[26:27], vcc
	s_cbranch_execz .LBB0_91
	v_or_b32_e32 v6, 16, v42
	v_ashrrev_i32_e32 v7, 31, v6
	v_lshlrev_b64 v[6:7], 13, v[6:7]
	v_lshl_add_u64 v[6:7], v[40:41], 0, v[6:7]
	global_load_dwordx4 v[6:9], v[6:7], off nt
.LBB0_91:
	s_or_b64 exec, exec, s[26:27]
	v_mov_b32_e32 v14, 0
	v_mov_b32_e32 v18, 0
	v_mov_b32_e32 v19, 0
	v_mov_b32_e32 v20, 0
	v_mov_b32_e32 v21, 0
	s_and_saveexec_b64 s[26:27], vcc
	s_cbranch_execz .LBB0_93
	v_or_b32_e32 v16, 24, v42
	v_ashrrev_i32_e32 v17, 31, v16
	v_lshlrev_b64 v[16:17], 13, v[16:17]
	v_lshl_add_u64 v[16:17], v[40:41], 0, v[16:17]
	global_load_dwordx4 v[18:21], v[16:17], off nt
.LBB0_93:
	s_or_b64 exec, exec, s[26:27]
	v_mov_b32_e32 v15, 0
	v_mov_b32_e32 v16, 0
	v_mov_b32_e32 v17, 0
	s_and_saveexec_b64 s[26:27], vcc
	s_cbranch_execz .LBB0_95
	v_or_b32_e32 v14, 32, v42
	v_ashrrev_i32_e32 v15, 31, v14
	v_lshlrev_b64 v[14:15], 13, v[14:15]
	v_lshl_add_u64 v[14:15], v[40:41], 0, v[14:15]
	global_load_dwordx4 v[14:17], v[14:15], off nt
.LBB0_95:
	s_or_b64 exec, exec, s[26:27]
	v_mov_b32_e32 v22, 0
	v_mov_b32_e32 v26, 0
	v_mov_b32_e32 v27, 0
	v_mov_b32_e32 v28, 0
	v_mov_b32_e32 v29, 0
	s_and_saveexec_b64 s[26:27], vcc
	s_cbranch_execz .LBB0_97
	v_or_b32_e32 v24, 40, v42
	v_ashrrev_i32_e32 v25, 31, v24
	v_lshlrev_b64 v[24:25], 13, v[24:25]
	v_lshl_add_u64 v[24:25], v[40:41], 0, v[24:25]
	global_load_dwordx4 v[26:29], v[24:25], off nt
.LBB0_97:
	s_or_b64 exec, exec, s[26:27]
	v_mov_b32_e32 v23, 0
	v_mov_b32_e32 v24, 0
	v_mov_b32_e32 v25, 0
	s_and_saveexec_b64 s[26:27], vcc
	s_cbranch_execz .LBB0_99
	v_or_b32_e32 v22, 48, v42
	v_ashrrev_i32_e32 v23, 31, v22
	v_lshlrev_b64 v[22:23], 13, v[22:23]
	v_lshl_add_u64 v[22:23], v[40:41], 0, v[22:23]
	global_load_dwordx4 v[22:25], v[22:23], off nt
.LBB0_99:
	s_or_b64 exec, exec, s[26:27]
	v_mov_b32_e32 v30, 0
	v_mov_b32_e32 v31, 0
	v_mov_b32_e32 v32, 0
	v_mov_b32_e32 v33, 0
	s_and_saveexec_b64 s[26:27], vcc
	s_cbranch_execz .LBB0_84
	v_or_b32_e32 v30, 56, v42
	v_ashrrev_i32_e32 v31, 31, v30
	v_lshlrev_b64 v[30:31], 13, v[30:31]
	v_lshl_add_u64 v[30:31], v[40:41], 0, v[30:31]
	global_load_dwordx4 v[30:33], v[30:31], off nt
	s_branch .LBB0_84

.LBB0_106:
	s_ashr_i32 s0, s26, 31
	s_lshr_b32 s0, s0, 27
	s_add_i32 s0, s26, s0
	s_ashr_i32 s0, s0, 5
	s_lshl_b32 s1, s0, 10
	s_sub_i32 s24, s3, s1
	s_lshl_b32 s8, s0, 6
	v_add_u32_e32 v2, s24, v36
	s_ashr_i32 s25, s24, 31
	v_cmp_gt_i32_e32 vcc, s5, v2
	v_or_b32_e32 v46, s8, v35
	v_lshl_add_u64 v[44:45], s[24:25], 2, v[40:41]
	v_mov_b32_e32 v2, 0
	v_mov_b32_e32 v3, 0
	v_mov_b32_e32 v4, 0
	v_mov_b32_e32 v5, 0
	s_and_saveexec_b64 s[24:25], vcc
	s_cbranch_execz .LBB0_108
	v_ashrrev_i32_e32 v47, 31, v46
	v_lshlrev_b64 v[2:3], 12, v[46:47]
	v_lshl_add_u64 v[2:3], v[44:45], 0, v[2:3]
	global_load_dwordx4 v[2:5], v[2:3], off nt
.LBB0_108:
	s_or_b64 exec, exec, s[24:25]
	v_mov_b32_e32 v6, 0
	v_mov_b32_e32 v10, 0
	v_mov_b32_e32 v11, 0
	v_mov_b32_e32 v12, 0
	v_mov_b32_e32 v13, 0
	s_and_saveexec_b64 s[24:25], vcc
	s_cbranch_execz .LBB0_110
	v_or_b32_e32 v8, 8, v46
	v_ashrrev_i32_e32 v9, 31, v8
	v_lshlrev_b64 v[8:9], 12, v[8:9]
	v_lshl_add_u64 v[8:9], v[44:45], 0, v[8:9]
	global_load_dwordx4 v[10:13], v[8:9], off nt
.LBB0_110:
	s_or_b64 exec, exec, s[24:25]
	v_mov_b32_e32 v7, 0
	v_mov_b32_e32 v8, 0
	v_mov_b32_e32 v9, 0
	s_and_saveexec_b64 s[24:25], vcc
	s_cbranch_execz .LBB0_112
	v_or_b32_e32 v6, 16, v46
	v_ashrrev_i32_e32 v7, 31, v6
	v_lshlrev_b64 v[6:7], 12, v[6:7]
	v_lshl_add_u64 v[6:7], v[44:45], 0, v[6:7]
	global_load_dwordx4 v[6:9], v[6:7], off nt
.LBB0_112:
	s_or_b64 exec, exec, s[24:25]
	v_mov_b32_e32 v14, 0
	v_mov_b32_e32 v18, 0
	v_mov_b32_e32 v19, 0
	v_mov_b32_e32 v20, 0
	v_mov_b32_e32 v21, 0
	s_and_saveexec_b64 s[24:25], vcc
	s_cbranch_execz .LBB0_114
	v_or_b32_e32 v16, 24, v46
	v_ashrrev_i32_e32 v17, 31, v16
	v_lshlrev_b64 v[16:17], 12, v[16:17]
	v_lshl_add_u64 v[16:17], v[44:45], 0, v[16:17]
	global_load_dwordx4 v[18:21], v[16:17], off nt
.LBB0_114:
	s_or_b64 exec, exec, s[24:25]
	v_mov_b32_e32 v15, 0
	v_mov_b32_e32 v16, 0
	v_mov_b32_e32 v17, 0
	s_and_saveexec_b64 s[24:25], vcc
	s_cbranch_execz .LBB0_116
	v_or_b32_e32 v14, 32, v46
	v_ashrrev_i32_e32 v15, 31, v14
	v_lshlrev_b64 v[14:15], 12, v[14:15]
	v_lshl_add_u64 v[14:15], v[44:45], 0, v[14:15]
	global_load_dwordx4 v[14:17], v[14:15], off nt
.LBB0_116:
	s_or_b64 exec, exec, s[24:25]
	v_mov_b32_e32 v22, 0
	v_mov_b32_e32 v26, 0
	v_mov_b32_e32 v27, 0
	v_mov_b32_e32 v28, 0
	v_mov_b32_e32 v29, 0
	s_and_saveexec_b64 s[24:25], vcc
	s_cbranch_execz .LBB0_118
	v_or_b32_e32 v24, 40, v46
	v_ashrrev_i32_e32 v25, 31, v24
	v_lshlrev_b64 v[24:25], 12, v[24:25]
	v_lshl_add_u64 v[24:25], v[44:45], 0, v[24:25]
	global_load_dwordx4 v[26:29], v[24:25], off nt
.LBB0_118:
	s_or_b64 exec, exec, s[24:25]
	v_mov_b32_e32 v23, 0
	v_mov_b32_e32 v24, 0
	v_mov_b32_e32 v25, 0
	s_and_saveexec_b64 s[24:25], vcc
	s_cbranch_execz .LBB0_120
	v_or_b32_e32 v22, 48, v46
	v_ashrrev_i32_e32 v23, 31, v22
	v_lshlrev_b64 v[22:23], 12, v[22:23]
	v_lshl_add_u64 v[22:23], v[44:45], 0, v[22:23]
	global_load_dwordx4 v[22:25], v[22:23], off nt
.LBB0_120:
	s_or_b64 exec, exec, s[24:25]
	v_mov_b32_e32 v30, 0
	v_mov_b32_e32 v31, 0
	v_mov_b32_e32 v32, 0
	v_mov_b32_e32 v33, 0
	s_and_saveexec_b64 s[24:25], vcc
	s_cbranch_execz .LBB0_105
	v_or_b32_e32 v30, 56, v46
	v_ashrrev_i32_e32 v31, 31, v30
	v_lshlrev_b64 v[30:31], 12, v[30:31]
	v_lshl_add_u64 v[30:31], v[44:45], 0, v[30:31]
	global_load_dwordx4 v[30:33], v[30:31], off nt
	s_branch .LBB0_105

.LBB0_127:
	s_ashr_i32 s0, s1, 31
	s_lshr_b32 s0, s0, 29
	s_add_i32 s0, s1, s0
	s_ashr_i32 s0, s0, 3
	s_lshl_b32 s26, s0, 6
	s_lshl_b32 s24, s0, 8
	v_or_b32_e32 v14, s26, v52
	s_sub_i32 s24, s41, s24
	v_or_b32_e32 v16, 8, v14
	v_or_b32_e32 v18, 16, v14
	v_or_b32_e32 v20, 24, v14
	v_or_b32_e32 v22, 32, v14
	v_or_b32_e32 v24, 40, v14
	v_or_b32_e32 v26, 48, v14
	v_or_b32_e32 v28, 56, v14
	s_ashr_i32 s25, s24, 31
	v_ashrrev_i32_e32 v15, 31, v14
	v_ashrrev_i32_e32 v17, 31, v16
	v_ashrrev_i32_e32 v19, 31, v18
	v_ashrrev_i32_e32 v21, 31, v20
	v_ashrrev_i32_e32 v23, 31, v22
	v_ashrrev_i32_e32 v25, 31, v24
	v_ashrrev_i32_e32 v27, 31, v26
	v_ashrrev_i32_e32 v29, 31, v28
	v_lshl_add_u64 v[30:31], s[24:25], 2, v[4:5]
	v_lshlrev_b64 v[14:15], 10, v[14:15]
	v_lshlrev_b64 v[32:33], 10, v[16:17]
	v_lshlrev_b64 v[18:19], 10, v[18:19]
	v_lshlrev_b64 v[20:21], 10, v[20:21]
	v_lshlrev_b64 v[22:23], 10, v[22:23]
	v_lshlrev_b64 v[24:25], 10, v[24:25]
	v_lshlrev_b64 v[26:27], 10, v[26:27]
	v_lshlrev_b64 v[28:29], 10, v[28:29]
	v_lshl_add_u64 v[14:15], v[30:31], 0, v[14:15]
	v_lshl_add_u64 v[32:33], v[30:31], 0, v[32:33]
	v_lshl_add_u64 v[42:43], v[30:31], 0, v[18:19]
	v_lshl_add_u64 v[44:45], v[30:31], 0, v[20:21]
	v_lshl_add_u64 v[46:47], v[30:31], 0, v[22:23]
	v_lshl_add_u64 v[48:49], v[30:31], 0, v[24:25]
	v_lshl_add_u64 v[62:63], v[30:31], 0, v[26:27]
	v_lshl_add_u64 v[64:65], v[30:31], 0, v[28:29]
	global_load_dwordx4 v[14:17], v[14:15], off nt
	s_nop 0
	global_load_dwordx4 v[18:21], v[32:33], off nt
	global_load_dwordx4 v[22:25], v[42:43], off nt
	global_load_dwordx4 v[26:29], v[44:45], off nt
	s_nop 0
	global_load_dwordx4 v[30:33], v[46:47], off nt
	global_load_dwordx4 v[42:45], v[48:49], off nt
	s_nop 0
	global_load_dwordx4 v[46:49], v[62:63], off nt
	s_nop 0
	global_load_dwordx4 v[62:65], v[64:65], off nt
	s_lshl_b32 s0, s0, 9
	s_sub_i32 s0, s40, s0
	s_and_b32 s0, s0, 0xffffff00
	s_and_b32 s24, s24, 0x60
	s_add_i32 s0, s0, s31
	s_or_b32 s0, s24, s0
	v_or_b32_e32 v68, s0, v52
	s_ashr_i32 s27, s26, 31
	v_ashrrev_i32_e32 v69, 31, v68
	v_lshl_add_u64 v[66:67], s[26:27], 1, v[2:3]
	v_lshlrev_b64 v[68:69], 9, v[68:69]
	v_lshl_add_u64 v[68:69], v[66:67], 0, v[68:69]
	v_or_b32_e32 v70, s0, v1
	v_ashrrev_i32_e32 v71, 31, v70
	v_lshlrev_b64 v[70:71], 9, v[70:71]
	v_lshl_add_u64 v[70:71], v[66:67], 0, v[70:71]
	v_or_b32_e32 v72, s0, v50
	v_ashrrev_i32_e32 v73, 31, v72
	v_lshlrev_b64 v[72:73], 9, v[72:73]
	v_lshl_add_u64 v[72:73], v[66:67], 0, v[72:73]
	v_or_b32_e32 v74, s0, v51
	v_ashrrev_i32_e32 v75, 31, v74
	v_lshlrev_b64 v[74:75], 9, v[74:75]
	s_add_i32 s1, s1, s33
	s_add_i32 s41, s41, s3
	s_add_i32 s40, s40, s30
	s_cmp_lt_i32 s1, 32
	s_waitcnt vmcnt(0)
	ds_write2_b32 v57, v14, v15 offset1:1
	ds_write2_b32 v57, v16, v17 offset0:2 offset1:3
	ds_write2_b32 v58, v18, v19 offset1:1
	ds_write2_b32 v58, v20, v21 offset0:2 offset1:3
	ds_write2_b32 v59, v22, v23 offset1:1
	ds_write2_b32 v59, v24, v25 offset0:2 offset1:3
	ds_write2_b32 v60, v26, v27 offset1:1
	ds_write2_b32 v60, v28, v29 offset0:2 offset1:3
	ds_write2_b32 v6, v30, v31 offset1:1
	ds_write2_b32 v7, v32, v33 offset1:1
	ds_write2_b32 v8, v42, v43 offset1:1
	ds_write2_b32 v9, v44, v45 offset1:1
	ds_write2_b32 v10, v46, v47 offset1:1
	ds_write2_b32 v11, v48, v49 offset1:1
	ds_write2_b32 v12, v62, v63 offset1:1
	ds_write2_b32 v13, v64, v65 offset1:1
	s_waitcnt lgkmcnt(0)
	ds_read2_b32 v[14:15], v53 offset1:33
	ds_read2_b32 v[16:17], v53 offset0:66 offset1:99
	ds_read2_b32 v[18:19], v53 offset0:132 offset1:165
	ds_read2_b32 v[20:21], v53 offset0:198 offset1:231
	v_lshl_add_u64 v[22:23], v[66:67], 0, v[74:75]
	s_waitcnt lgkmcnt(0)
	v_cvt_pk_bf16_f32 v14, v14, v15
	s_waitcnt lgkmcnt(2)
	v_cvt_pk_bf16_f32 v15, v16, v17
	s_waitcnt lgkmcnt(1)
	v_cvt_pk_bf16_f32 v16, v18, v19
	s_waitcnt lgkmcnt(0)
	v_cvt_pk_bf16_f32 v17, v20, v21
	flat_store_dwordx4 v[68:69], v[14:17]
	ds_read2_b32 v[14:15], v54 offset1:33
	ds_read2_b32 v[16:17], v54 offset0:66 offset1:99
	ds_read2_b32 v[18:19], v54 offset0:132 offset1:165
	ds_read2_b32 v[20:21], v54 offset0:198 offset1:231
	s_waitcnt lgkmcnt(0)
	v_cvt_pk_bf16_f32 v14, v14, v15
	v_cvt_pk_bf16_f32 v15, v16, v17
	v_cvt_pk_bf16_f32 v16, v18, v19
	v_cvt_pk_bf16_f32 v17, v20, v21
	flat_store_dwordx4 v[70:71], v[14:17]
	ds_read2_b32 v[14:15], v55 offset1:33
	ds_read2_b32 v[16:17], v55 offset0:66 offset1:99
	ds_read2_b32 v[18:19], v55 offset0:132 offset1:165
	ds_read2_b32 v[20:21], v55 offset0:198 offset1:231
	s_waitcnt lgkmcnt(0)
	v_cvt_pk_bf16_f32 v14, v14, v15
	v_cvt_pk_bf16_f32 v15, v16, v17
	v_cvt_pk_bf16_f32 v16, v18, v19
	v_cvt_pk_bf16_f32 v17, v20, v21
	flat_store_dwordx4 v[72:73], v[14:17]
	ds_read2_b32 v[14:15], v56 offset1:33
	ds_read2_b32 v[16:17], v56 offset0:66 offset1:99
	ds_read2_b32 v[18:19], v56 offset0:132 offset1:165
	ds_read2_b32 v[20:21], v56 offset0:198 offset1:231
	s_waitcnt lgkmcnt(0)
	v_cvt_pk_bf16_f32 v14, v14, v15
	v_cvt_pk_bf16_f32 v15, v16, v17
	v_cvt_pk_bf16_f32 v16, v18, v19
	v_cvt_pk_bf16_f32 v17, v20, v21
	flat_store_dwordx4 v[22:23], v[14:17]
	s_waitcnt lgkmcnt(0)
	s_cbranch_scc1 .LBB0_127
	s_branch .LBB0_124

.LBB0_131:
	s_mul_hi_i32 s0, s27, 0x2aaaaaab
	s_lshr_b32 s1, s0, 31
	s_ashr_i32 s0, s0, 2
	s_add_i32 s0, s0, s1
	s_lshl_b32 s10, s0, 6
	s_mulk_i32 s0, 0xfd00
	s_add_i32 s8, s4, s0
	v_add_u32_e32 v2, s8, v36
	s_ashr_i32 s9, s8, 31
	v_cmp_gt_i32_e32 vcc, s5, v2
	v_or_b32_e32 v35, s10, v52
	v_lshl_add_u64 v[46:47], s[8:9], 2, v[42:43]
	v_mov_b32_e32 v2, 0
	v_mov_b32_e32 v6, 0
	v_mov_b32_e32 v7, 0
	v_mov_b32_e32 v8, 0
	v_mov_b32_e32 v9, 0
	s_and_saveexec_b64 s[24:25], vcc
	s_cbranch_execz .LBB0_133
	v_mad_i64_i32 v[4:5], s[0:1], v35, s26, v[46:47]
	global_load_dwordx4 v[6:9], v[4:5], off nt
.LBB0_133:
	s_or_b64 exec, exec, s[24:25]
	v_mov_b32_e32 v3, 0
	v_mov_b32_e32 v4, 0
	v_mov_b32_e32 v5, 0
	s_and_saveexec_b64 s[24:25], vcc
	s_cbranch_execz .LBB0_135
	v_or_b32_e32 v2, 8, v35
	v_mad_i64_i32 v[2:3], s[0:1], v2, s26, v[46:47]
	global_load_dwordx4 v[2:5], v[2:3], off nt
.LBB0_135:
	s_or_b64 exec, exec, s[24:25]
	v_mov_b32_e32 v10, 0
	v_mov_b32_e32 v14, 0
	v_mov_b32_e32 v15, 0
	v_mov_b32_e32 v16, 0
	v_mov_b32_e32 v17, 0
	s_and_saveexec_b64 s[24:25], vcc
	s_cbranch_execz .LBB0_137
	v_or_b32_e32 v11, 16, v35
	v_mad_i64_i32 v[12:13], s[0:1], v11, s26, v[46:47]
	global_load_dwordx4 v[14:17], v[12:13], off nt
.LBB0_137:
	s_or_b64 exec, exec, s[24:25]
	v_mov_b32_e32 v11, 0
	v_mov_b32_e32 v12, 0
	v_mov_b32_e32 v13, 0
	s_and_saveexec_b64 s[24:25], vcc
	s_cbranch_execz .LBB0_139
	v_or_b32_e32 v10, 24, v35
	v_mad_i64_i32 v[10:11], s[0:1], v10, s26, v[46:47]
	global_load_dwordx4 v[10:13], v[10:11], off nt
.LBB0_139:
	s_or_b64 exec, exec, s[24:25]
	v_mov_b32_e32 v18, 0
	v_mov_b32_e32 v22, 0
	v_mov_b32_e32 v23, 0
	v_mov_b32_e32 v24, 0
	v_mov_b32_e32 v25, 0
	s_and_saveexec_b64 s[24:25], vcc
	s_cbranch_execz .LBB0_141
	v_or_b32_e32 v19, 32, v35
	v_mad_i64_i32 v[20:21], s[0:1], v19, s26, v[46:47]
	global_load_dwordx4 v[22:25], v[20:21], off nt
.LBB0_141:
	s_or_b64 exec, exec, s[24:25]
	v_mov_b32_e32 v19, 0
	v_mov_b32_e32 v20, 0
	v_mov_b32_e32 v21, 0
	s_and_saveexec_b64 s[24:25], vcc
	s_cbranch_execz .LBB0_143
	v_or_b32_e32 v18, 40, v35
	v_mad_i64_i32 v[18:19], s[0:1], v18, s26, v[46:47]
	global_load_dwordx4 v[18:21], v[18:19], off nt
.LBB0_143:
	s_or_b64 exec, exec, s[24:25]
	v_mov_b32_e32 v26, 0
	v_mov_b32_e32 v30, 0
	v_mov_b32_e32 v31, 0
	v_mov_b32_e32 v32, 0
	v_mov_b32_e32 v33, 0
	s_and_saveexec_b64 s[24:25], vcc
	s_cbranch_execz .LBB0_145
	v_or_b32_e32 v27, 48, v35
	v_mad_i64_i32 v[28:29], s[0:1], v27, s26, v[46:47]
	global_load_dwordx4 v[30:33], v[28:29], off nt
.LBB0_145:
	s_or_b64 exec, exec, s[24:25]
	v_mov_b32_e32 v27, 0
	v_mov_b32_e32 v28, 0
	v_mov_b32_e32 v29, 0
	s_and_saveexec_b64 s[24:25], vcc
	s_cbranch_execz .LBB0_130
	v_or_b32_e32 v26, 56, v35
	v_mad_i64_i32 v[26:27], s[0:1], v26, s26, v[46:47]
	global_load_dwordx4 v[26:29], v[26:27], off nt
	s_branch .LBB0_130

.LBB0_150:
	s_mul_hi_i32 s0, s27, 0x2aaaaaab
	s_lshr_b32 s1, s0, 31
	s_ashr_i32 s0, s0, 3
	s_add_i32 s0, s0, s1
	s_mul_i32 s1, s0, 0xfffffa00
	s_lshl_b32 s8, s0, 6
	s_add_i32 s10, s4, s1
	v_or_b32_e32 v29, s8, v52
	s_ashr_i32 s11, s10, 31
	v_lshl_add_u64 v[6:7], s[10:11], 2, v[2:3]
	v_or_b32_e32 v8, 8, v29
	v_mad_i64_i32 v[30:31], s[10:11], v29, s20, v[6:7]
	v_mad_i64_i32 v[32:33], s[10:11], v8, s20, v[6:7]
	v_or_b32_e32 v35, 32, v29
	global_load_dwordx4 v[8:11], v[30:31], off nt
	global_load_dwordx4 v[12:15], v[32:33], off nt
	v_or_b32_e32 v30, 16, v29
	v_or_b32_e32 v32, 24, v29
	v_mad_i64_i32 v[46:47], s[10:11], v35, s20, v[6:7]
	v_or_b32_e32 v35, 40, v29
	v_mad_i64_i32 v[30:31], s[10:11], v30, s20, v[6:7]
	v_mad_i64_i32 v[42:43], s[10:11], v32, s20, v[6:7]
	v_mad_i64_i32 v[62:63], s[10:11], v35, s20, v[6:7]
	global_load_dwordx4 v[30:33], v[30:31], off nt
	s_nop 0
	global_load_dwordx4 v[42:45], v[42:43], off nt
	s_nop 0
	global_load_dwordx4 v[46:49], v[46:47], off nt
	s_nop 0
	global_load_dwordx4 v[62:65], v[62:63], off nt
	v_or_b32_e32 v35, 48, v29
	v_mad_i64_i32 v[66:67], s[10:11], v35, s20, v[6:7]
	global_load_dwordx4 v[66:69], v[66:67], off nt
	v_or_b32_e32 v29, 56, v29
	v_mad_i64_i32 v[6:7], s[10:11], v29, s20, v[6:7]
	global_load_dwordx4 v[70:73], v[6:7], off nt
	v_add_u32_e32 v7, s4, v52
	v_add_u32_e32 v6, s1, v7
	v_mul_hi_i32 v6, v6, s5
	v_lshrrev_b32_e32 v29, 31, v6
	v_ashrrev_i32_e32 v6, 5, v6
	v_add_u32_e32 v6, v6, v29
	v_mul_lo_u32 v29, v6, s21
	s_mulk_i32 s0, 0x600
	v_subrev_u32_e32 v29, s0, v29
	s_waitcnt vmcnt(0)
	ds_write2_b32 v57, v8, v9 offset1:1
	ds_write2_b32 v57, v10, v11 offset0:2 offset1:3
	ds_write2_b32 v58, v12, v13 offset1:1
	ds_write2_b32 v58, v14, v15 offset0:2 offset1:3
	ds_write2_b32 v59, v30, v31 offset1:1
	ds_write2_b32 v59, v32, v33 offset0:2 offset1:3
	ds_write2_b32 v60, v42, v43 offset1:1
	ds_write2_b32 v60, v44, v45 offset0:2 offset1:3
	ds_write2_b32 v20, v46, v47 offset1:1
	ds_write2_b32 v21, v48, v49 offset1:1
	ds_write2_b32 v22, v62, v63 offset1:1
	ds_write2_b32 v23, v64, v65 offset1:1
	ds_write2_b32 v24, v66, v67 offset1:1
	ds_write2_b32 v25, v68, v69 offset1:1
	ds_write2_b32 v26, v70, v71 offset1:1
	ds_write2_b32 v27, v72, v73 offset1:1
	s_waitcnt lgkmcnt(0)
	ds_read2_b32 v[8:9], v53 offset1:33
	ds_read2_b32 v[10:11], v53 offset0:66 offset1:99
	ds_read2_b32 v[12:13], v53 offset0:132 offset1:165
	ds_read2_b32 v[14:15], v53 offset0:198 offset1:231
	v_add_u32_e32 v30, v7, v29
	v_cmp_lt_i32_e32 vcc, s24, v30
	s_and_saveexec_b64 s[10:11], vcc
	s_xor_b64 s[10:11], exec, s[10:11]
	v_lshlrev_b32_e32 v7, 6, v6
	v_and_b32_e32 v7, 0xffffff00, v7
	v_lshl_add_u32 v29, v30, 2, v28
	v_lshlrev_b32_e32 v6, 5, v6
	v_add_u32_e32 v7, v16, v7
	v_and_b32_e32 v29, 0x7fffff80, v29
	v_and_or_b32 v6, v6, s25, v7
	v_add_u32_e32 v29, v6, v29
	s_andn2_saveexec_b64 s[10:11], s[10:11]
	v_lshl_add_u32 v6, v6, 6, s0
	v_sub_u32_e32 v29, v7, v6
	s_or_b64 exec, exec, s[10:11]
	s_ashr_i32 s9, s8, 31
	v_lshl_add_u64 v[6:7], s[8:9], 1, v[4:5]
	s_waitcnt lgkmcnt(0)
	v_cvt_pk_bf16_f32 v8, v8, v9
	v_cvt_pk_bf16_f32 v9, v10, v11
	v_cvt_pk_bf16_f32 v10, v12, v13
	v_cvt_pk_bf16_f32 v11, v14, v15
	v_mad_i64_i32 v[12:13], s[8:9], v29, s26, v[6:7]
	v_add_u32_e32 v31, s4, v1
	flat_store_dwordx4 v[12:13], v[8:11]
	v_add_u32_e32 v29, s1, v31
	ds_read2_b32 v[8:9], v54 offset1:33
	ds_read2_b32 v[10:11], v54 offset0:66 offset1:99
	ds_read2_b32 v[12:13], v54 offset0:132 offset1:165
	ds_read2_b32 v[14:15], v54 offset0:198 offset1:231
	v_mul_hi_i32 v29, v29, s5
	v_lshrrev_b32_e32 v30, 31, v29
	v_ashrrev_i32_e32 v29, 5, v29
	v_add_u32_e32 v30, v29, v30
	v_mul_lo_u32 v29, v30, s21
	v_subrev_u32_e32 v29, s0, v29
	v_add_u32_e32 v32, v31, v29
	v_cmp_lt_i32_e32 vcc, s24, v32
	s_and_saveexec_b64 s[8:9], vcc
	s_xor_b64 s[8:9], exec, s[8:9]
	v_lshlrev_b32_e32 v29, 6, v30
	v_and_b32_e32 v29, 0xffffff00, v29
	v_lshl_add_u32 v31, v32, 2, v28
	v_lshlrev_b32_e32 v30, 5, v30
	v_add_u32_e32 v29, v17, v29
	v_and_b32_e32 v31, 0x7fffff80, v31
	v_and_or_b32 v29, v30, s25, v29
	v_add_u32_e32 v29, v29, v31
	s_andn2_saveexec_b64 s[8:9], s[8:9]
	v_lshl_add_u32 v29, v30, 6, s0
	v_sub_u32_e32 v29, v31, v29
	s_or_b64 exec, exec, s[8:9]
	s_waitcnt lgkmcnt(0)
	v_cvt_pk_bf16_f32 v8, v8, v9
	v_cvt_pk_bf16_f32 v9, v10, v11
	v_cvt_pk_bf16_f32 v10, v12, v13
	v_cvt_pk_bf16_f32 v11, v14, v15
	v_mad_i64_i32 v[12:13], s[8:9], v29, s26, v[6:7]
	v_add_u32_e32 v31, s4, v50
	flat_store_dwordx4 v[12:13], v[8:11]
	v_add_u32_e32 v29, s1, v31
	ds_read2_b32 v[8:9], v55 offset1:33
	ds_read2_b32 v[10:11], v55 offset0:66 offset1:99
	ds_read2_b32 v[12:13], v55 offset0:132 offset1:165
	ds_read2_b32 v[14:15], v55 offset0:198 offset1:231
	v_mul_hi_i32 v29, v29, s5
	v_lshrrev_b32_e32 v30, 31, v29
	v_ashrrev_i32_e32 v29, 5, v29
	v_add_u32_e32 v30, v29, v30
	v_mul_lo_u32 v29, v30, s21
	v_subrev_u32_e32 v29, s0, v29
	v_add_u32_e32 v32, v31, v29
	v_cmp_lt_i32_e32 vcc, s24, v32
	s_and_saveexec_b64 s[8:9], vcc
	s_xor_b64 s[8:9], exec, s[8:9]
	v_lshlrev_b32_e32 v29, 6, v30
	v_and_b32_e32 v29, 0xffffff00, v29
	v_lshl_add_u32 v31, v32, 2, v28
	v_lshlrev_b32_e32 v30, 5, v30
	v_add_u32_e32 v29, v18, v29
	v_and_b32_e32 v31, 0x7fffff80, v31
	v_and_or_b32 v29, v30, s25, v29
	v_add_u32_e32 v29, v29, v31
	s_andn2_saveexec_b64 s[8:9], s[8:9]
	v_lshl_add_u32 v29, v30, 6, s0
	v_sub_u32_e32 v29, v31, v29
	s_or_b64 exec, exec, s[8:9]
	s_waitcnt lgkmcnt(0)
	v_cvt_pk_bf16_f32 v8, v8, v9
	v_cvt_pk_bf16_f32 v9, v10, v11
	v_cvt_pk_bf16_f32 v10, v12, v13
	v_cvt_pk_bf16_f32 v11, v14, v15
	v_mad_i64_i32 v[12:13], s[8:9], v29, s26, v[6:7]
	v_add_u32_e32 v31, s4, v51
	flat_store_dwordx4 v[12:13], v[8:11]
	v_add_u32_e32 v29, s1, v31
	ds_read2_b32 v[8:9], v56 offset1:33
	ds_read2_b32 v[10:11], v56 offset0:66 offset1:99
	ds_read2_b32 v[12:13], v56 offset0:132 offset1:165
	ds_read2_b32 v[14:15], v56 offset0:198 offset1:231
	v_mul_hi_i32 v29, v29, s5
	v_lshrrev_b32_e32 v30, 31, v29
	v_ashrrev_i32_e32 v29, 5, v29
	v_add_u32_e32 v30, v29, v30
	v_mul_lo_u32 v29, v30, s21
	v_subrev_u32_e32 v29, s0, v29
	v_add_u32_e32 v32, v31, v29
	v_cmp_lt_i32_e32 vcc, s24, v32
	s_and_saveexec_b64 s[8:9], vcc
	s_xor_b64 s[8:9], exec, s[8:9]
	v_lshlrev_b32_e32 v29, 6, v30
	v_and_b32_e32 v29, 0xffffff00, v29
	v_lshl_add_u32 v31, v32, 2, v28
	v_lshlrev_b32_e32 v30, 5, v30
	v_add_u32_e32 v29, v19, v29
	v_and_b32_e32 v31, 0x7fffff80, v31
	v_and_or_b32 v29, v30, s25, v29
	v_add_u32_e32 v29, v29, v31
	s_andn2_saveexec_b64 s[8:9], s[8:9]
	s_cbranch_execz .LBB0_149
	v_lshl_add_u32 v29, v30, 6, s0
	v_sub_u32_e32 v29, v31, v29
	s_branch .LBB0_149

.LBB0_169:
	s_ashr_i32 s0, s20, 31
	s_lshr_b32 s0, s0, 26
	s_add_i32 s0, s20, s0
	s_and_b32 s8, s0, 0xffffffc0
	s_lshl_b32 s0, s0, 5
	s_and_b32 s1, s0, 0xfffff800
	s_sub_i32 s10, s4, s1
	v_add_u32_e32 v2, s10, v36
	s_ashr_i32 s11, s10, 31
	v_cmp_gt_i32_e32 vcc, s5, v2
	v_or_b32_e32 v48, s8, v52
	v_lshl_add_u64 v[46:47], s[10:11], 2, v[42:43]
	v_mov_b32_e32 v2, 0
	v_mov_b32_e32 v6, 0
	v_mov_b32_e32 v7, 0
	v_mov_b32_e32 v8, 0
	v_mov_b32_e32 v9, 0
	s_and_saveexec_b64 s[10:11], vcc
	s_cbranch_execz .LBB0_171
	v_ashrrev_i32_e32 v49, 31, v48
	v_lshlrev_b64 v[4:5], 13, v[48:49]
	v_lshl_add_u64 v[4:5], v[46:47], 0, v[4:5]
	global_load_dwordx4 v[6:9], v[4:5], off nt
.LBB0_171:
	s_or_b64 exec, exec, s[10:11]
	v_mov_b32_e32 v3, 0
	v_mov_b32_e32 v4, 0
	v_mov_b32_e32 v5, 0
	s_and_saveexec_b64 s[10:11], vcc
	s_cbranch_execz .LBB0_173
	v_or_b32_e32 v2, 8, v48
	v_ashrrev_i32_e32 v3, 31, v2
	v_lshlrev_b64 v[2:3], 13, v[2:3]
	v_lshl_add_u64 v[2:3], v[46:47], 0, v[2:3]
	global_load_dwordx4 v[2:5], v[2:3], off nt
.LBB0_173:
	s_or_b64 exec, exec, s[10:11]
	v_mov_b32_e32 v10, 0
	v_mov_b32_e32 v14, 0
	v_mov_b32_e32 v15, 0
	v_mov_b32_e32 v16, 0
	v_mov_b32_e32 v17, 0
	s_and_saveexec_b64 s[10:11], vcc
	s_cbranch_execz .LBB0_175
	v_or_b32_e32 v12, 16, v48
	v_ashrrev_i32_e32 v13, 31, v12
	v_lshlrev_b64 v[12:13], 13, v[12:13]
	v_lshl_add_u64 v[12:13], v[46:47], 0, v[12:13]
	global_load_dwordx4 v[14:17], v[12:13], off nt
.LBB0_175:
	s_or_b64 exec, exec, s[10:11]
	v_mov_b32_e32 v11, 0
	v_mov_b32_e32 v12, 0
	v_mov_b32_e32 v13, 0
	s_and_saveexec_b64 s[10:11], vcc
	s_cbranch_execz .LBB0_177
	v_or_b32_e32 v10, 24, v48
	v_ashrrev_i32_e32 v11, 31, v10
	v_lshlrev_b64 v[10:11], 13, v[10:11]
	v_lshl_add_u64 v[10:11], v[46:47], 0, v[10:11]
	global_load_dwordx4 v[10:13], v[10:11], off nt
.LBB0_177:
	s_or_b64 exec, exec, s[10:11]
	v_mov_b32_e32 v18, 0
	v_mov_b32_e32 v22, 0
	v_mov_b32_e32 v23, 0
	v_mov_b32_e32 v24, 0
	v_mov_b32_e32 v25, 0
	s_and_saveexec_b64 s[10:11], vcc
	s_cbranch_execz .LBB0_179
	v_or_b32_e32 v20, 32, v48
	v_ashrrev_i32_e32 v21, 31, v20
	v_lshlrev_b64 v[20:21], 13, v[20:21]
	v_lshl_add_u64 v[20:21], v[46:47], 0, v[20:21]
	global_load_dwordx4 v[22:25], v[20:21], off nt
.LBB0_179:
	s_or_b64 exec, exec, s[10:11]
	v_mov_b32_e32 v19, 0
	v_mov_b32_e32 v20, 0
	v_mov_b32_e32 v21, 0
	s_and_saveexec_b64 s[10:11], vcc
	s_cbranch_execz .LBB0_181
	v_or_b32_e32 v18, 40, v48
	v_ashrrev_i32_e32 v19, 31, v18
	v_lshlrev_b64 v[18:19], 13, v[18:19]
	v_lshl_add_u64 v[18:19], v[46:47], 0, v[18:19]
	global_load_dwordx4 v[18:21], v[18:19], off nt
.LBB0_181:
	s_or_b64 exec, exec, s[10:11]
	v_mov_b32_e32 v26, 0
	v_mov_b32_e32 v30, 0
	v_mov_b32_e32 v31, 0
	v_mov_b32_e32 v32, 0
	v_mov_b32_e32 v33, 0
	s_and_saveexec_b64 s[10:11], vcc
	s_cbranch_execz .LBB0_183
	v_or_b32_e32 v28, 48, v48
	v_ashrrev_i32_e32 v29, 31, v28
	v_lshlrev_b64 v[28:29], 13, v[28:29]
	v_lshl_add_u64 v[28:29], v[46:47], 0, v[28:29]
	global_load_dwordx4 v[30:33], v[28:29], off nt
.LBB0_183:
	s_or_b64 exec, exec, s[10:11]
	v_mov_b32_e32 v27, 0
	v_mov_b32_e32 v28, 0
	v_mov_b32_e32 v29, 0
	s_and_saveexec_b64 s[10:11], vcc
	s_cbranch_execz .LBB0_168
	v_or_b32_e32 v26, 56, v48
	v_ashrrev_i32_e32 v27, 31, v26
	v_lshlrev_b64 v[26:27], 13, v[26:27]
	v_lshl_add_u64 v[26:27], v[46:47], 0, v[26:27]
	global_load_dwordx4 v[26:29], v[26:27], off nt
	s_branch .LBB0_168

.LBB0_188:
	s_ashr_i32 s0, s10, 31
	s_lshr_b32 s0, s0, 27
	s_add_i32 s0, s10, s0
	s_ashr_i32 s0, s0, 5
	s_lshl_b32 s1, s0, 10
	s_sub_i32 s8, s4, s1
	s_lshl_b32 s6, s0, 6
	v_add_u32_e32 v2, s8, v36
	s_ashr_i32 s9, s8, 31
	v_cmp_gt_i32_e32 vcc, s5, v2
	v_or_b32_e32 v46, s6, v52
	v_lshl_add_u64 v[44:45], s[8:9], 2, v[42:43]
	v_mov_b32_e32 v2, 0
	v_mov_b32_e32 v6, 0
	v_mov_b32_e32 v7, 0
	v_mov_b32_e32 v8, 0
	v_mov_b32_e32 v9, 0
	s_and_saveexec_b64 s[8:9], vcc
	s_cbranch_execz .LBB0_190
	v_ashrrev_i32_e32 v47, 31, v46
	v_lshlrev_b64 v[4:5], 12, v[46:47]
	v_lshl_add_u64 v[4:5], v[44:45], 0, v[4:5]
	global_load_dwordx4 v[6:9], v[4:5], off nt
.LBB0_190:
	s_or_b64 exec, exec, s[8:9]
	v_mov_b32_e32 v3, 0
	v_mov_b32_e32 v4, 0
	v_mov_b32_e32 v5, 0
	s_and_saveexec_b64 s[8:9], vcc
	s_cbranch_execz .LBB0_192
	v_or_b32_e32 v2, 8, v46
	v_ashrrev_i32_e32 v3, 31, v2
	v_lshlrev_b64 v[2:3], 12, v[2:3]
	v_lshl_add_u64 v[2:3], v[44:45], 0, v[2:3]
	global_load_dwordx4 v[2:5], v[2:3], off nt
.LBB0_192:
	s_or_b64 exec, exec, s[8:9]
	v_mov_b32_e32 v10, 0
	v_mov_b32_e32 v14, 0
	v_mov_b32_e32 v15, 0
	v_mov_b32_e32 v16, 0
	v_mov_b32_e32 v17, 0
	s_and_saveexec_b64 s[8:9], vcc
	s_cbranch_execz .LBB0_194
	v_or_b32_e32 v12, 16, v46
	v_ashrrev_i32_e32 v13, 31, v12
	v_lshlrev_b64 v[12:13], 12, v[12:13]
	v_lshl_add_u64 v[12:13], v[44:45], 0, v[12:13]
	global_load_dwordx4 v[14:17], v[12:13], off nt
.LBB0_194:
	s_or_b64 exec, exec, s[8:9]
	v_mov_b32_e32 v11, 0
	v_mov_b32_e32 v12, 0
	v_mov_b32_e32 v13, 0
	s_and_saveexec_b64 s[8:9], vcc
	s_cbranch_execz .LBB0_196
	v_or_b32_e32 v10, 24, v46
	v_ashrrev_i32_e32 v11, 31, v10
	v_lshlrev_b64 v[10:11], 12, v[10:11]
	v_lshl_add_u64 v[10:11], v[44:45], 0, v[10:11]
	global_load_dwordx4 v[10:13], v[10:11], off nt
.LBB0_196:
	s_or_b64 exec, exec, s[8:9]
	v_mov_b32_e32 v18, 0
	v_mov_b32_e32 v22, 0
	v_mov_b32_e32 v23, 0
	v_mov_b32_e32 v24, 0
	v_mov_b32_e32 v25, 0
	s_and_saveexec_b64 s[8:9], vcc
	s_cbranch_execz .LBB0_198
	v_or_b32_e32 v20, 32, v46
	v_ashrrev_i32_e32 v21, 31, v20
	v_lshlrev_b64 v[20:21], 12, v[20:21]
	v_lshl_add_u64 v[20:21], v[44:45], 0, v[20:21]
	global_load_dwordx4 v[22:25], v[20:21], off nt
.LBB0_198:
	s_or_b64 exec, exec, s[8:9]
	v_mov_b32_e32 v19, 0
	v_mov_b32_e32 v20, 0
	v_mov_b32_e32 v21, 0
	s_and_saveexec_b64 s[8:9], vcc
	s_cbranch_execz .LBB0_200
	v_or_b32_e32 v18, 40, v46
	v_ashrrev_i32_e32 v19, 31, v18
	v_lshlrev_b64 v[18:19], 12, v[18:19]
	v_lshl_add_u64 v[18:19], v[44:45], 0, v[18:19]
	global_load_dwordx4 v[18:21], v[18:19], off nt
.LBB0_200:
	s_or_b64 exec, exec, s[8:9]
	v_mov_b32_e32 v26, 0
	v_mov_b32_e32 v30, 0
	v_mov_b32_e32 v31, 0
	v_mov_b32_e32 v32, 0
	v_mov_b32_e32 v33, 0
	s_and_saveexec_b64 s[8:9], vcc
	s_cbranch_execz .LBB0_202
	v_or_b32_e32 v28, 48, v46
	v_ashrrev_i32_e32 v29, 31, v28
	v_lshlrev_b64 v[28:29], 12, v[28:29]
	v_lshl_add_u64 v[28:29], v[44:45], 0, v[28:29]
	global_load_dwordx4 v[30:33], v[28:29], off nt
.LBB0_202:
	s_or_b64 exec, exec, s[8:9]
	v_mov_b32_e32 v27, 0
	v_mov_b32_e32 v28, 0
	v_mov_b32_e32 v29, 0
	s_and_saveexec_b64 s[8:9], vcc
	s_cbranch_execz .LBB0_187
	v_or_b32_e32 v26, 56, v46
	v_ashrrev_i32_e32 v27, 31, v26
	v_lshlrev_b64 v[26:27], 12, v[26:27]
	v_lshl_add_u64 v[26:27], v[44:45], 0, v[26:27]
	global_load_dwordx4 v[26:29], v[26:27], off nt
	s_branch .LBB0_187

.LBB0_206:
	global_load_dwordx4 v[10:13], v[4:5], off nt
	v_lshl_add_u64 v[8:9], v[8:9], 0, s[6:7]
	v_cmp_lt_u64_e32 vcc, s[22:23], v[8:9]
	v_lshl_add_u64 v[4:5], v[4:5], 0, s[10:11]
	s_or_b64 s[20:21], vcc, s[20:21]
	s_waitcnt vmcnt(0)
	v_cvt_pk_bf16_f32 v10, v10, v11
	v_cvt_pk_bf16_f32 v11, v12, v13
	flat_store_dwordx2 v[6:7], v[10:11]
	v_lshl_add_u64 v[6:7], v[6:7], 0, s[16:17]
	s_andn2_b64 exec, exec, s[20:21]
	s_cbranch_execnz .LBB0_206

.LBB0_213:
	s_mul_hi_i32 s0, s18, 0x2aaaaaab
	s_lshr_b32 s1, s0, 31
	s_ashr_i32 s0, s0, 8
	s_add_i32 s8, s0, s1
	s_mul_i32 s0, s8, 0xfffffa00
	s_add_i32 s21, s18, s0
	s_lshr_b32 s0, s21, 22
	s_and_b32 s0, s0, 0x1ff
	s_add_i32 s22, s21, s0
	s_and_b32 s0, s22, 0xfe00
	s_sub_i32 s0, s21, s0
	s_sext_i32_i16 s1, s0
	s_bfe_u32 s1, s1, 0x5001a
	s_add_i32 s1, s0, s1
	s_sext_i32_i16 s6, s1
	s_and_b32 s1, s1, 0xffe0
	s_lshl_b32 s20, s6, 1
	s_sub_i32 s0, s0, s1
	s_andn2_b32 s20, s20, 63
	s_sext_i32_i16 s19, s0
	s_lshl_b32 s6, s19, 5
	v_or_b32_e32 v16, s20, v52
	s_mov_b64 s[10:11], -1
	s_cmpk_gt_i32 s21, 0x3ff
	v_ashrrev_i32_e32 v17, 31, v16
	v_or_b32_e32 v14, 8, v16
	v_or_b32_e32 v12, 16, v16
	v_or_b32_e32 v10, 24, v16
	v_or_b32_e32 v8, 32, v16
	v_or_b32_e32 v6, 40, v16
	v_or_b32_e32 v4, 48, v16
	v_or_b32_e32 v2, 56, v16
	s_cbranch_scc0 .LBB0_215
	s_ashr_i32 s9, s8, 31
	s_lshl_b64 s[0:1], s[8:9], 20
	s_lshl_b64 s[10:11], s[8:9], 22
	s_add_u32 s9, s34, s10
	s_addc_u32 s10, s35, s11
	s_add_u32 s11, s5, s0
	s_addc_u32 s23, s16, s1
	s_ashr_i32 s7, s6, 31
	s_lshl_b64 s[0:1], s[6:7], 2
	s_add_u32 s0, s9, s0
	s_addc_u32 s1, s10, s1
	v_lshl_add_u64 v[48:49], v[36:37], 2, s[0:1]
	v_lshlrev_b64 v[28:29], 12, v[16:17]
	v_ashrrev_i32_e32 v15, 31, v14
	v_lshl_add_u64 v[40:41], v[48:49], 0, v[28:29]
	v_lshlrev_b64 v[28:29], 12, v[14:15]
	v_ashrrev_i32_e32 v13, 31, v12
	v_lshl_add_u64 v[42:43], v[48:49], 0, v[28:29]
	global_load_dwordx4 v[28:31], v[40:41], off nt
	global_load_dwordx4 v[32:35], v[42:43], off nt
	v_lshlrev_b64 v[40:41], 12, v[12:13]
	v_ashrrev_i32_e32 v11, 31, v10
	v_lshl_add_u64 v[62:63], v[48:49], 0, v[40:41]
	v_lshlrev_b64 v[40:41], 12, v[10:11]
	v_ashrrev_i32_e32 v9, 31, v8
	v_lshl_add_u64 v[64:65], v[48:49], 0, v[40:41]
	global_load_dwordx4 v[40:43], v[62:63], off nt
	global_load_dwordx4 v[44:47], v[64:65], off nt
	v_lshlrev_b64 v[62:63], 12, v[8:9]
	v_ashrrev_i32_e32 v7, 31, v6
	v_lshl_add_u64 v[70:71], v[48:49], 0, v[62:63]
	v_lshlrev_b64 v[62:63], 12, v[6:7]
	v_lshl_add_u64 v[72:73], v[48:49], 0, v[62:63]
	global_load_dwordx4 v[62:65], v[70:71], off nt
	global_load_dwordx4 v[66:69], v[72:73], off nt
	v_ashrrev_i32_e32 v5, 31, v4
	v_lshlrev_b64 v[70:71], 12, v[4:5]
	v_lshl_add_u64 v[70:71], v[48:49], 0, v[70:71]
	v_ashrrev_i32_e32 v3, 31, v2
	global_load_dwordx4 v[70:73], v[70:71], off nt
	v_lshlrev_b64 v[74:75], 12, v[2:3]
	v_lshl_add_u64 v[48:49], v[48:49], 0, v[74:75]
	global_load_dwordx4 v[74:77], v[48:49], off nt
	v_mov_b32_e32 v48, 0
	v_mov_b32_e32 v49, 0
	s_ashr_i32 s1, s20, 31
	v_or_b32_e32 v78, s6, v52
	s_add_u32 s0, s11, s20
	v_ashrrev_i32_e32 v79, 31, v78
	s_addc_u32 s1, s23, s1
	v_lshlrev_b64 v[78:79], 10, v[78:79]
	v_mov_b32_e32 v80, 0
	v_mov_b32_e32 v81, 0
	s_waitcnt vmcnt(0)
	ds_write2_b32 v57, v28, v29 offset1:1
	ds_write2_b32 v57, v30, v31 offset0:2 offset1:3
	ds_write2_b32 v58, v32, v33 offset1:1
	ds_write2_b32 v58, v34, v35 offset0:2 offset1:3
	ds_write2_b32 v59, v40, v41 offset1:1
	ds_write2_b32 v59, v42, v43 offset0:2 offset1:3
	ds_write2_b32 v60, v44, v45 offset1:1
	ds_write2_b32 v60, v46, v47 offset0:2 offset1:3
	ds_write2_b32 v18, v62, v63 offset1:1
	ds_write2_b32 v19, v64, v65 offset1:1
	ds_write2_b32 v20, v66, v67 offset1:1
	ds_write2_b32 v21, v68, v69 offset1:1
	ds_write2_b32 v22, v70, v71 offset1:1
	ds_write2_b32 v23, v72, v73 offset1:1
	ds_write2_b32 v24, v74, v75 offset1:1
	ds_write2_b32 v25, v76, v77 offset1:1
	s_waitcnt lgkmcnt(0)
	ds_read2_b32 v[28:29], v53 offset1:33
	ds_read2_b32 v[30:31], v53 offset0:66 offset1:99
	ds_read2_b32 v[32:33], v53 offset0:132 offset1:165
	ds_read2_b32 v[34:35], v53 offset0:198 offset1:231
	s_waitcnt lgkmcnt(0)
	v_mul_f32_e32 v7, 0x43000000, v30
	v_mul_f32_e32 v3, 0x43000000, v28
	v_mul_f32_e32 v5, 0x43000000, v29
	v_mul_f32_e32 v11, 0x43000000, v32
	v_mul_f32_e32 v13, 0x43000000, v33
	v_med3_f32 v3, v3, s17, v26
	v_med3_f32 v5, v5, s17, v26
	v_med3_f32 v11, v11, s17, v26
	v_med3_f32 v13, v13, s17, v26
	v_cvt_pk_fp8_f32 v48, v3, v5
	v_cvt_pk_fp8_f32 v49, v11, v13
	v_mul_f32_e32 v9, 0x43000000, v31
	v_mul_f32_e32 v15, 0x43000000, v34
	v_mul_f32_e32 v27, 0x43000000, v35
	v_med3_f32 v7, v7, s17, v26
	v_med3_f32 v9, v9, s17, v26
	v_med3_f32 v3, v15, s17, v26
	v_med3_f32 v5, v27, s17, v26
	v_cvt_pk_fp8_f32 v48, v7, v9 op_sel:[0,0,1]
	v_cvt_pk_fp8_f32 v49, v3, v5 op_sel:[0,0,1]
	v_lshl_add_u64 v[28:29], s[0:1], 0, v[38:39]
	v_lshl_add_u64 v[30:31], v[28:29], 0, v[78:79]
	flat_store_dwordx2 v[30:31], v[48:49]
	ds_read2_b32 v[30:31], v54 offset1:33
	ds_read2_b32 v[32:33], v54 offset0:66 offset1:99
	ds_read2_b32 v[34:35], v54 offset0:132 offset1:165
	ds_read2_b32 v[40:41], v54 offset0:198 offset1:231
	s_waitcnt lgkmcnt(0)
	v_mul_f32_e32 v7, 0x43000000, v32
	v_mul_f32_e32 v3, 0x43000000, v30
	v_mul_f32_e32 v5, 0x43000000, v31
	v_mul_f32_e32 v11, 0x43000000, v34
	v_mul_f32_e32 v13, 0x43000000, v35
	v_med3_f32 v3, v3, s17, v26
	v_med3_f32 v5, v5, s17, v26
	v_med3_f32 v11, v11, s17, v26
	v_med3_f32 v13, v13, s17, v26
	v_cvt_pk_fp8_f32 v80, v3, v5
	v_cvt_pk_fp8_f32 v81, v11, v13
	v_mul_f32_e32 v9, 0x43000000, v33
	v_mul_f32_e32 v15, 0x43000000, v40
	v_mul_f32_e32 v27, 0x43000000, v41
	v_med3_f32 v7, v7, s17, v26
	v_med3_f32 v9, v9, s17, v26
	v_med3_f32 v3, v15, s17, v26
	v_med3_f32 v5, v27, s17, v26
	v_cvt_pk_fp8_f32 v80, v7, v9 op_sel:[0,0,1]
	v_cvt_pk_fp8_f32 v81, v3, v5 op_sel:[0,0,1]
	v_or_b32_e32 v30, s6, v1
	v_ashrrev_i32_e32 v31, 31, v30
	v_lshlrev_b64 v[30:31], 10, v[30:31]
	v_lshl_add_u64 v[30:31], v[28:29], 0, v[30:31]
	flat_store_dwordx2 v[30:31], v[80:81]
	ds_read2_b32 v[30:31], v55 offset1:33
	ds_read2_b32 v[32:33], v55 offset0:66 offset1:99
	ds_read2_b32 v[34:35], v55 offset0:198 offset1:231
	s_waitcnt lgkmcnt(0)
	v_mul_f32_e32 v3, 0x43000000, v30
	v_mul_f32_e32 v5, 0x43000000, v31
	v_mul_f32_e32 v7, 0x43000000, v32
	v_mul_f32_e32 v9, 0x43000000, v33
	v_med3_f32 v3, v3, s17, v26
	v_med3_f32 v5, v5, s17, v26
	v_mov_b32_e32 v30, 0
	ds_read2_b32 v[32:33], v55 offset0:132 offset1:165
	v_cvt_pk_fp8_f32 v30, v3, v5
	v_med3_f32 v3, v7, s17, v26
	v_med3_f32 v5, v9, s17, v26
	v_mov_b32_e32 v31, 0
	v_cvt_pk_fp8_f32 v30, v3, v5 op_sel:[0,0,1]
	s_waitcnt lgkmcnt(0)
	v_mul_f32_e32 v3, 0x43000000, v32
	v_mul_f32_e32 v5, 0x43000000, v33
	v_med3_f32 v3, v3, s17, v26
	v_med3_f32 v5, v5, s17, v26
	v_cvt_pk_fp8_f32 v31, v3, v5
	v_mul_f32_e32 v7, 0x43000000, v34
	v_mul_f32_e32 v3, 0x43000000, v35
	v_med3_f32 v5, v7, s17, v26
	v_med3_f32 v3, v3, s17, v26
	v_cvt_pk_fp8_f32 v31, v5, v3 op_sel:[0,0,1]
	v_or_b32_e32 v32, s6, v50
	v_ashrrev_i32_e32 v33, 31, v32
	v_lshlrev_b64 v[32:33], 10, v[32:33]
	v_lshl_add_u64 v[32:33], v[28:29], 0, v[32:33]
	flat_store_dwordx2 v[32:33], v[30:31]
	ds_read2_b32 v[30:31], v56 offset1:33
	ds_read2_b32 v[32:33], v56 offset0:66 offset1:99
	ds_read2_b32 v[34:35], v56 offset0:198 offset1:231
	s_waitcnt lgkmcnt(0)
	v_mul_f32_e32 v3, 0x43000000, v30
	v_mul_f32_e32 v5, 0x43000000, v31
	v_mul_f32_e32 v7, 0x43000000, v32
	v_mul_f32_e32 v9, 0x43000000, v33
	v_med3_f32 v3, v3, s17, v26
	v_med3_f32 v5, v5, s17, v26
	v_mov_b32_e32 v30, 0
	ds_read2_b32 v[32:33], v56 offset0:132 offset1:165
	v_cvt_pk_fp8_f32 v30, v3, v5
	v_med3_f32 v3, v7, s17, v26
	v_med3_f32 v5, v9, s17, v26
	v_mov_b32_e32 v31, 0
	v_cvt_pk_fp8_f32 v30, v3, v5 op_sel:[0,0,1]
	s_waitcnt lgkmcnt(0)
	v_mul_f32_e32 v3, 0x43000000, v32
	v_mul_f32_e32 v5, 0x43000000, v33
	v_med3_f32 v3, v3, s17, v26
	v_med3_f32 v5, v5, s17, v26
	v_cvt_pk_fp8_f32 v31, v3, v5
	v_mul_f32_e32 v7, 0x43000000, v34
	v_mul_f32_e32 v3, 0x43000000, v35
	v_med3_f32 v5, v7, s17, v26
	v_med3_f32 v3, v3, s17, v26
	v_cvt_pk_fp8_f32 v31, v5, v3 op_sel:[0,0,1]
	v_or_b32_e32 v32, s6, v51
	v_ashrrev_i32_e32 v33, 31, v32
	v_lshlrev_b64 v[32:33], 10, v[32:33]
	v_lshl_add_u64 v[28:29], v[28:29], 0, v[32:33]
	flat_store_dwordx2 v[28:29], v[30:31]
	s_waitcnt lgkmcnt(0)
	s_cbranch_execnz .LBB0_212
	s_branch .LBB0_216

.LBB0_216:
	s_sext_i32_i16 s0, s22
	s_lshr_b32 s10, s0, 9
	s_addk_i32 s21, 0x1ff
	s_cmpk_lt_u32 s21, 0x3ff
	s_cselect_b32 s7, s13, s15
	s_cselect_b32 s11, s12, s14
	s_ashr_i32 s9, s8, 31
	s_lshl_b64 s[0:1], s[8:9], 22
	s_add_u32 s11, s11, s0
	s_addc_u32 s21, s7, s1
	s_lshl_b64 s[0:1], s[8:9], 21
	s_add_u32 s8, s3, s0
	s_addc_u32 s9, s4, s1
	s_ashr_i32 s7, s6, 31
	s_lshl_b64 s[0:1], s[6:7], 2
	s_add_u32 s0, s11, s0
	s_addc_u32 s1, s21, s1
	v_ashrrev_i32_e32 v15, 31, v14
	v_ashrrev_i32_e32 v13, 31, v12
	v_ashrrev_i32_e32 v11, 31, v10
	v_ashrrev_i32_e32 v9, 31, v8
	v_lshl_add_u64 v[48:49], v[36:37], 2, s[0:1]
	v_lshlrev_b64 v[16:17], 12, v[16:17]
	v_lshlrev_b64 v[14:15], 12, v[14:15]
	v_lshlrev_b64 v[12:13], 12, v[12:13]
	v_lshlrev_b64 v[10:11], 12, v[10:11]
	v_lshlrev_b64 v[8:9], 12, v[8:9]
	v_ashrrev_i32_e32 v7, 31, v6
	v_lshl_add_u64 v[32:33], v[48:49], 0, v[16:17]
	v_lshl_add_u64 v[34:35], v[48:49], 0, v[14:15]
	v_lshl_add_u64 v[40:41], v[48:49], 0, v[12:13]
	v_lshl_add_u64 v[42:43], v[48:49], 0, v[10:11]
	v_lshl_add_u64 v[44:45], v[48:49], 0, v[8:9]
	v_lshlrev_b64 v[6:7], 12, v[6:7]
	global_load_dwordx4 v[14:17], v[32:33], off nt
	global_load_dwordx4 v[28:31], v[34:35], off nt
	global_load_dwordx4 v[10:13], v[40:41], off nt
	s_nop 0
	global_load_dwordx4 v[32:35], v[42:43], off nt
	v_lshl_add_u64 v[46:47], v[48:49], 0, v[6:7]
	global_load_dwordx4 v[6:9], v[44:45], off nt
	global_load_dwordx4 v[40:43], v[46:47], off nt
	v_ashrrev_i32_e32 v5, 31, v4
	v_lshlrev_b64 v[4:5], 12, v[4:5]
	v_lshl_add_u64 v[4:5], v[48:49], 0, v[4:5]
	v_ashrrev_i32_e32 v3, 31, v2
	global_load_dwordx4 v[44:47], v[4:5], off nt
	v_lshlrev_b64 v[2:3], 12, v[2:3]
	v_lshl_add_u64 v[2:3], v[48:49], 0, v[2:3]
	global_load_dwordx4 v[2:5], v[2:3], off nt
	s_sext_i32_i16 s0, s10
	s_lshl_b32 s7, s0, 7
	s_ashr_i32 s1, s20, 31
	v_mov_b32_e32 v48, 0
	v_mov_b32_e32 v49, 0
	s_add_u32 s0, s8, s20
	s_addc_u32 s1, s9, s1
	s_lshl_b32 s8, s19, 6
	v_lshl_add_u64 v[62:63], s[0:1], 0, v[38:39]
	s_and_b32 s0, s8, 0xffffff00
	s_and_b32 s6, s6, 0x60
	s_add_i32 s0, s0, s7
	s_or_b32 s0, s0, s6
	s_waitcnt vmcnt(0)
	ds_write2_b32 v57, v14, v15 offset1:1
	ds_write2_b32 v57, v16, v17 offset0:2 offset1:3
	ds_write2_b32 v58, v28, v29 offset1:1
	ds_write2_b32 v58, v30, v31 offset0:2 offset1:3
	ds_write2_b32 v59, v10, v11 offset1:1
	ds_write2_b32 v59, v12, v13 offset0:2 offset1:3
	ds_write2_b32 v60, v32, v33 offset1:1
	ds_write2_b32 v60, v34, v35 offset0:2 offset1:3
	ds_write2_b32 v18, v6, v7 offset1:1
	ds_write2_b32 v19, v8, v9 offset1:1
	ds_write2_b32 v20, v40, v41 offset1:1
	ds_write2_b32 v21, v42, v43 offset1:1
	ds_write2_b32 v22, v44, v45 offset1:1
	ds_write2_b32 v23, v46, v47 offset1:1
	ds_write2_b32 v24, v2, v3 offset1:1
	ds_write2_b32 v25, v4, v5 offset1:1
	s_waitcnt lgkmcnt(0)
	ds_read2_b32 v[2:3], v53 offset1:33
	ds_read2_b32 v[6:7], v53 offset0:66 offset1:99
	ds_read2_b32 v[8:9], v53 offset0:132 offset1:165
	ds_read2_b32 v[10:11], v53 offset0:198 offset1:231
	v_or_b32_e32 v4, s0, v52
	s_waitcnt lgkmcnt(0)
	v_mul_f32_e32 v5, 0x42800000, v6
	v_mul_f32_e32 v2, 0x42800000, v2
	v_mul_f32_e32 v3, 0x42800000, v3
	v_mul_f32_e32 v6, 0x42800000, v7
	v_mul_f32_e32 v7, 0x42800000, v8
	v_mul_f32_e32 v8, 0x42800000, v9
	v_med3_f32 v2, v2, s17, v26
	v_med3_f32 v3, v3, s17, v26
	v_med3_f32 v7, v7, s17, v26
	v_med3_f32 v8, v8, s17, v26
	v_cvt_pk_fp8_f32 v48, v2, v3
	v_cvt_pk_fp8_f32 v49, v7, v8
	v_mul_f32_e32 v9, 0x42800000, v10
	v_mul_f32_e32 v10, 0x42800000, v11
	v_med3_f32 v5, v5, s17, v26
	v_med3_f32 v6, v6, s17, v26
	v_med3_f32 v2, v9, s17, v26
	v_med3_f32 v3, v10, s17, v26
	v_cvt_pk_fp8_f32 v48, v5, v6 op_sel:[0,0,1]
	v_cvt_pk_fp8_f32 v49, v2, v3 op_sel:[0,0,1]
	v_ashrrev_i32_e32 v5, 31, v4
	v_lshlrev_b64 v[2:3], 10, v[4:5]
	v_lshl_add_u64 v[2:3], v[62:63], 0, v[2:3]
	flat_store_dwordx2 v[2:3], v[48:49]
	ds_read2_b32 v[2:3], v54 offset1:33
	v_mov_b32_e32 v4, 0
	ds_read2_b32 v[6:7], v54 offset0:66 offset1:99
	ds_read2_b32 v[8:9], v54 offset0:132 offset1:165
	ds_read2_b32 v[10:11], v54 offset0:198 offset1:231
	s_waitcnt lgkmcnt(0)
	v_mul_f32_e32 v2, 0x42800000, v2
	v_mul_f32_e32 v3, 0x42800000, v3
	v_med3_f32 v2, v2, s17, v26
	v_med3_f32 v3, v3, s17, v26
	v_cvt_pk_fp8_f32 v4, v2, v3
	v_mul_f32_e32 v5, 0x42800000, v6
	v_mul_f32_e32 v6, 0x42800000, v7
	v_med3_f32 v3, v5, s17, v26
	v_med3_f32 v5, v6, s17, v26
	v_mul_f32_e32 v2, 0x42800000, v8
	v_cvt_pk_fp8_f32 v4, v3, v5 op_sel:[0,0,1]
	v_mul_f32_e32 v3, 0x42800000, v9
	v_med3_f32 v2, v2, s17, v26
	v_med3_f32 v3, v3, s17, v26
	v_mov_b32_e32 v5, 0
	v_cvt_pk_fp8_f32 v5, v2, v3
	v_mul_f32_e32 v6, 0x42800000, v10
	v_mul_f32_e32 v2, 0x42800000, v11
	v_med3_f32 v3, v6, s17, v26
	v_med3_f32 v2, v2, s17, v26
	v_cvt_pk_fp8_f32 v5, v3, v2 op_sel:[0,0,1]
	v_or_b32_e32 v2, s0, v1
	v_ashrrev_i32_e32 v3, 31, v2
	v_lshlrev_b64 v[2:3], 10, v[2:3]
	v_lshl_add_u64 v[2:3], v[62:63], 0, v[2:3]
	flat_store_dwordx2 v[2:3], v[4:5]
	ds_read2_b32 v[2:3], v55 offset1:33
	ds_read2_b32 v[4:5], v55 offset0:66 offset1:99
	s_waitcnt lgkmcnt(0)
	v_mul_f32_e32 v2, 0x42800000, v2
	v_mul_f32_e32 v3, 0x42800000, v3
	v_mul_f32_e32 v6, 0x42800000, v4
	v_med3_f32 v4, v2, s17, v26
	v_med3_f32 v3, v3, s17, v26
	v_mov_b32_e32 v2, 0
	v_mul_f32_e32 v8, 0x42800000, v5
	v_cvt_pk_fp8_f32 v2, v4, v3
	ds_read2_b32 v[4:5], v55 offset0:132 offset1:165
	v_med3_f32 v3, v6, s17, v26
	ds_read2_b32 v[6:7], v55 offset0:198 offset1:231
	v_med3_f32 v8, v8, s17, v26
	v_cvt_pk_fp8_f32 v2, v3, v8 op_sel:[0,0,1]
	s_waitcnt lgkmcnt(0)
	v_mul_f32_e32 v3, 0x42800000, v4
	v_mul_f32_e32 v4, 0x42800000, v5
	v_mul_f32_e32 v5, 0x42800000, v6
	v_med3_f32 v6, v3, s17, v26
	v_med3_f32 v4, v4, s17, v26
	v_mov_b32_e32 v3, 0
	v_cvt_pk_fp8_f32 v3, v6, v4
	v_mul_f32_e32 v4, 0x42800000, v7
	v_med3_f32 v5, v5, s17, v26
	v_med3_f32 v4, v4, s17, v26
	v_cvt_pk_fp8_f32 v3, v5, v4 op_sel:[0,0,1]
	v_or_b32_e32 v4, s0, v50
	v_ashrrev_i32_e32 v5, 31, v4
	v_lshlrev_b64 v[4:5], 10, v[4:5]
	v_lshl_add_u64 v[4:5], v[62:63], 0, v[4:5]
	flat_store_dwordx2 v[4:5], v[2:3]
	ds_read2_b32 v[2:3], v56 offset1:33
	ds_read2_b32 v[4:5], v56 offset0:66 offset1:99
	s_waitcnt lgkmcnt(0)
	v_mul_f32_e32 v2, 0x42800000, v2
	v_mul_f32_e32 v3, 0x42800000, v3
	v_mul_f32_e32 v6, 0x42800000, v4
	v_med3_f32 v4, v2, s17, v26
	v_med3_f32 v3, v3, s17, v26
	v_mov_b32_e32 v2, 0
	v_mul_f32_e32 v8, 0x42800000, v5
	v_cvt_pk_fp8_f32 v2, v4, v3
	ds_read2_b32 v[4:5], v56 offset0:132 offset1:165
	v_med3_f32 v3, v6, s17, v26
	ds_read2_b32 v[6:7], v56 offset0:198 offset1:231
	v_med3_f32 v8, v8, s17, v26
	v_cvt_pk_fp8_f32 v2, v3, v8 op_sel:[0,0,1]
	s_waitcnt lgkmcnt(0)
	v_mul_f32_e32 v3, 0x42800000, v4
	v_mul_f32_e32 v4, 0x42800000, v5
	v_mul_f32_e32 v5, 0x42800000, v6
	v_med3_f32 v6, v3, s17, v26
	v_med3_f32 v4, v4, s17, v26
	v_mov_b32_e32 v3, 0
	v_cvt_pk_fp8_f32 v3, v6, v4
	v_mul_f32_e32 v4, 0x42800000, v7
	v_med3_f32 v5, v5, s17, v26
	v_med3_f32 v4, v4, s17, v26
	v_cvt_pk_fp8_f32 v3, v5, v4 op_sel:[0,0,1]
	v_or_b32_e32 v4, s0, v51
	v_ashrrev_i32_e32 v5, 31, v4
	v_lshlrev_b64 v[4:5], 10, v[4:5]
	v_lshl_add_u64 v[4:5], v[62:63], 0, v[4:5]
	flat_store_dwordx2 v[4:5], v[2:3]
	s_waitcnt lgkmcnt(0)
	s_branch .LBB0_212

.LBB0_813:
	s_or_b64 exec, exec, s[8:9]
	s_waitcnt lgkmcnt(0)
	s_barrier
	s_load_dwordx8 s[12:19], s[84:85], 0xd8
	s_load_dwordx4 s[4:7], s[84:85], 0xf8
	s_load_dwordx2 s[20:21], s[84:85], 0x108
	s_add_i32 s8, s33, s68
	s_ashr_i32 s69, s68, 31
	s_ashr_i32 s9, s8, 31
	s_mov_b32 s0, s8
	s_lshl_b64 s[24:25], s[68:69], 11
	v_writelane_b32 v253, s0, 34
	s_lshl_b64 s[26:27], s[8:9], 11
	v_mov_b32_e32 v39, v0
	s_waitcnt lgkmcnt(0)
	s_mov_b32 s8, s21
	v_writelane_b32 v253, s1, 35
	s_mov_b32 s0, s7
	v_and_b32_e32 v74, 63, v39
	s_add_u32 s22, s20, 0x3e00000
	s_addc_u32 s23, s8, 0
	v_lshlrev_b32_e32 v34, 4, v74
	v_mov_b32_e32 v35, 0
	v_lshl_add_u64 v[2:3], s[18:19], 0, v[34:35]
	s_mov_b64 s[0:1], 0x1000
	v_lshl_add_u64 v[6:7], s[4:5], 0, v[34:35]
	s_add_u32 s18, s20, 0x3900000
	v_lshl_add_u64 v[26:27], v[2:3], 0, s[0:1]
	v_lshl_add_u64 v[30:31], v[6:7], 0, s[0:1]
	s_movk_i32 s0, 0x1000
	s_addc_u32 s19, s8, 0
	v_add_co_u32_e32 v2, vcc, s0, v2
	s_add_u32 s10, s20, 0xa100000
	s_nop 0
	v_addc_co_u32_e32 v3, vcc, 0, v3, vcc
	s_addc_u32 s11, s8, 0
	v_add_co_u32_e32 v6, vcc, s0, v6
	s_add_u32 s0, s10, s24
	v_writelane_b32 v253, s24, 36
	s_addc_u32 s1, s11, s25
	s_add_u32 s4, s10, s26
	v_writelane_b32 v253, s25, 37
	v_lshlrev_b32_e32 v34, 3, v74
	v_addc_co_u32_e32 v7, vcc, 0, v7, vcc
	v_writelane_b32 v253, s26, 38
	s_addc_u32 s5, s11, s27
	v_lshl_add_u64 v[36:37], s[0:1], 0, v[34:35]
	global_load_dwordx4 v[2:5], v[2:3], off nt
	s_nop 0
	global_load_dwordx4 v[6:9], v[6:7], off nt
	s_nop 0
	global_load_dwordx4 v[10:13], v[26:27], off offset:1024
	global_load_dwordx4 v[14:17], v[26:27], off offset:2048
	global_load_dwordx4 v[18:21], v[30:31], off offset:1024
	global_load_dwordx4 v[22:25], v[30:31], off offset:2048
	s_nop 0
	global_load_dwordx4 v[26:29], v[26:27], off offset:3072
	s_nop 0
	global_load_dwordx4 v[30:33], v[30:31], off offset:3072
	v_lshl_add_u64 v[46:47], s[4:5], 0, v[34:35]
	flat_load_dwordx2 v[64:65], v[36:37]
	flat_load_dwordx2 v[62:63], v[36:37] offset:512
	flat_load_dwordx2 v[60:61], v[36:37] offset:1024
	flat_load_dwordx2 v[58:59], v[36:37] offset:1536
	flat_load_dwordx2 v[44:45], v[46:47]
	flat_load_dwordx2 v[42:43], v[46:47] offset:512
	flat_load_dwordx2 v[40:41], v[46:47] offset:1024
	s_nop 0
	flat_load_dwordx2 v[36:37], v[46:47] offset:1536
	s_mov_b32 s7, s8
	v_cmp_gt_u32_e64 s[8:9], 16, v74
	v_mov_b32_e32 v75, -1
	v_lshlrev_b32_e32 v38, 11, v74
	v_mov_b32_e32 v82, v35
	v_mov_b32_e32 v81, -1
	v_writelane_b32 v253, s27, 39
	s_and_saveexec_b64 s[24:25], s[8:9]
	s_cbranch_execz .LBB0_815
	v_readlane_b32 s0, v253, 34
	v_readlane_b32 s1, v253, 35
	s_mov_b32 s4, s0
	s_ashr_i32 s0, s0, 11
	s_ashr_i32 s1, s0, 31
	s_lshl_b64 s[0:1], s[0:1], 15
	s_and_b32 s4, s4, 0x7ff
	s_or_b32 s0, s0, s4
	s_ashr_i32 s4, s68, 11
	s_ashr_i32 s5, s4, 31
	s_lshl_b64 s[4:5], s[4:5], 15
	s_and_b32 s6, s68, 0x7ff
	s_or_b32 s4, s4, s6
	v_or_b32_e32 v46, s4, v38
	v_mov_b32_e32 v47, s5
	v_lshl_add_u64 v[48:49], v[46:47], 1, s[22:23]
	v_lshl_add_u64 v[46:47], v[46:47], 2, s[18:19]
	flat_load_sshort v81, v[48:49]
	flat_load_dword v82, v[46:47]
	v_or_b32_e32 v46, s0, v38
	v_mov_b32_e32 v47, s1
	v_lshl_add_u64 v[48:49], v[46:47], 1, s[22:23]
	v_lshl_add_u64 v[46:47], v[46:47], 2, s[18:19]
	flat_load_sshort v75, v[48:49]
	flat_load_dword v35, v[46:47]

.LBB0_830:
	s_mul_hi_i32 s0, s21, 0x2aaaaaab
	s_lshr_b32 s1, s0, 31
	s_ashr_i32 s0, s0, 8
	s_add_i32 s16, s0, s1
	s_mul_i32 s0, s16, 0xfffffa00
	s_add_i32 s24, s21, s0
	s_lshr_b32 s0, s24, 22
	s_and_b32 s0, s0, 0x1ff
	s_add_i32 s25, s24, s0
	s_and_b32 s0, s25, 0xfe00
	s_sub_i32 s0, s24, s0
	s_sext_i32_i16 s1, s0
	s_bfe_u32 s1, s1, 0x5001a
	s_add_i32 s1, s0, s1
	s_sext_i32_i16 s8, s1
	s_and_b32 s1, s1, 0xffe0
	s_lshl_b32 s23, s8, 1
	s_sub_i32 s0, s0, s1
	s_andn2_b32 s23, s23, 63
	s_sext_i32_i16 s22, s0
	s_lshl_b32 s8, s22, 5
	v_or_b32_e32 v20, s23, v26
	s_mov_b64 s[18:19], -1
	s_cmpk_gt_i32 s24, 0x3ff
	v_ashrrev_i32_e32 v21, 31, v20
	v_or_b32_e32 v18, 8, v20
	v_or_b32_e32 v16, 16, v20
	v_or_b32_e32 v14, 24, v20
	v_or_b32_e32 v12, 32, v20
	v_or_b32_e32 v10, 40, v20
	v_or_b32_e32 v8, 48, v20
	v_or_b32_e32 v6, 56, v20
	s_cbranch_scc0 .LBB0_832
	s_ashr_i32 s17, s16, 31
	s_lshl_b64 s[0:1], s[16:17], 20
	s_lshl_b64 s[18:19], s[16:17], 22
	s_add_u32 s17, s10, s18
	s_addc_u32 s18, s11, s19
	s_add_u32 s19, s6, s0
	s_addc_u32 s26, s7, s1
	s_ashr_i32 s9, s8, 31
	s_lshl_b64 s[0:1], s[8:9], 2
	s_add_u32 s0, s17, s0
	s_addc_u32 s1, s18, s1
	v_lshl_add_u64 v[72:73], s[0:1], 0, v[2:3]
	v_lshlrev_b64 v[22:23], 12, v[20:21]
	v_lshl_add_u64 v[22:23], v[72:73], 0, v[22:23]
	v_ashrrev_i32_e32 v19, 31, v18
	global_load_dwordx4 v[22:25], v[22:23], off nt
	v_lshlrev_b64 v[48:49], 12, v[18:19]
	v_lshl_add_u64 v[48:49], v[72:73], 0, v[48:49]
	v_ashrrev_i32_e32 v17, 31, v16
	global_load_dwordx4 v[48:51], v[48:49], off nt
	v_lshlrev_b64 v[52:53], 12, v[16:17]
	v_lshl_add_u64 v[52:53], v[72:73], 0, v[52:53]
	v_ashrrev_i32_e32 v15, 31, v14
	global_load_dwordx4 v[52:55], v[52:53], off nt
	v_lshlrev_b64 v[56:57], 12, v[14:15]
	v_lshl_add_u64 v[56:57], v[72:73], 0, v[56:57]
	v_ashrrev_i32_e32 v13, 31, v12
	global_load_dwordx4 v[56:59], v[56:57], off nt
	v_lshlrev_b64 v[60:61], 12, v[12:13]
	v_lshl_add_u64 v[60:61], v[72:73], 0, v[60:61]
	v_ashrrev_i32_e32 v11, 31, v10
	global_load_dwordx4 v[60:63], v[60:61], off nt
	v_lshlrev_b64 v[64:65], 12, v[10:11]
	v_lshl_add_u64 v[64:65], v[72:73], 0, v[64:65]
	v_ashrrev_i32_e32 v9, 31, v8
	global_load_dwordx4 v[64:67], v[64:65], off nt
	v_lshlrev_b64 v[68:69], 12, v[8:9]
	v_lshl_add_u64 v[68:69], v[72:73], 0, v[68:69]
	v_ashrrev_i32_e32 v7, 31, v6
	global_load_dwordx4 v[68:71], v[68:69], off nt
	v_lshlrev_b64 v[74:75], 12, v[6:7]
	v_lshl_add_u64 v[72:73], v[72:73], 0, v[74:75]
	global_load_dwordx4 v[72:75], v[72:73], off nt
	s_ashr_i32 s1, s23, 31
	s_add_u32 s0, s19, s23
	s_addc_u32 s1, s26, s1
	s_waitcnt vmcnt(0)
	ds_write2_b32 v31, v22, v23 offset1:1
	ds_write2_b32 v31, v24, v25 offset0:2 offset1:3
	s_waitcnt vmcnt(6)
	ds_write2_b32 v32, v48, v49 offset1:1
	ds_write2_b32 v33, v50, v51 offset1:1
	s_waitcnt vmcnt(5)
	ds_write2_b32 v34, v52, v53 offset1:1
	ds_write2_b32 v35, v54, v55 offset1:1
	s_waitcnt vmcnt(4)
	ds_write2_b32 v36, v56, v57 offset1:1
	ds_write2_b32 v37, v58, v59 offset1:1
	s_waitcnt vmcnt(3)
	ds_write2_b32 v38, v60, v61 offset1:1
	ds_write2_b32 v39, v62, v63 offset1:1
	s_waitcnt vmcnt(2)
	ds_write2_b32 v40, v64, v65 offset1:1
	ds_write2_b32 v41, v66, v67 offset1:1
	s_waitcnt vmcnt(1)
	ds_write2_b32 v42, v68, v69 offset1:1
	ds_write2_b32 v43, v70, v71 offset1:1
	s_waitcnt vmcnt(0)
	ds_write2_b32 v44, v72, v73 offset1:1
	ds_write2_b32 v45, v74, v75 offset1:1
	s_waitcnt lgkmcnt(0)
	ds_read_b32 v7, v30
	ds_read_b32 v9, v30 offset:132
	ds_read_b32 v11, v30 offset:264
	ds_read_b32 v13, v30 offset:396
	v_mov_b32_e32 v24, v3
	s_waitcnt lgkmcnt(0)
	v_mul_f32_e32 v7, 0x43000000, v7
	s_waitcnt lgkmcnt(2)
	v_mul_f32_e32 v9, 0x43000000, v9
	v_med3_f32 v7, v7, s20, v46
	v_med3_f32 v9, v9, s20, v46
	v_cvt_pk_fp8_f32 v24, v7, v9
	s_waitcnt lgkmcnt(1)
	v_mul_f32_e32 v11, 0x43000000, v11
	s_waitcnt lgkmcnt(0)
	v_mul_f32_e32 v13, 0x43000000, v13
	v_med3_f32 v7, v11, s20, v46
	v_med3_f32 v9, v13, s20, v46
	v_cvt_pk_fp8_f32 v24, v7, v9 op_sel:[0,0,1]
	ds_read_b32 v7, v30 offset:528
	ds_read_b32 v9, v30 offset:660
	ds_read_b32 v11, v30 offset:792
	ds_read_b32 v13, v30 offset:924
	v_mov_b32_e32 v25, v3
	s_waitcnt lgkmcnt(3)
	v_mul_f32_e32 v7, 0x43000000, v7
	s_waitcnt lgkmcnt(2)
	v_mul_f32_e32 v9, 0x43000000, v9
	v_med3_f32 v7, v7, s20, v46
	v_med3_f32 v9, v9, s20, v46
	v_cvt_pk_fp8_f32 v25, v7, v9
	s_waitcnt lgkmcnt(1)
	v_mul_f32_e32 v11, 0x43000000, v11
	s_waitcnt lgkmcnt(0)
	v_mul_f32_e32 v13, 0x43000000, v13
	v_med3_f32 v7, v11, s20, v46
	v_med3_f32 v9, v13, s20, v46
	v_cvt_pk_fp8_f32 v25, v7, v9 op_sel:[0,0,1]
	v_or_b32_e32 v48, s8, v26
	v_ashrrev_i32_e32 v49, 31, v48
	v_lshl_add_u64 v[22:23], s[0:1], 0, v[4:5]
	v_lshlrev_b64 v[48:49], 10, v[48:49]
	v_lshl_add_u64 v[48:49], v[22:23], 0, v[48:49]
	flat_store_dwordx2 v[48:49], v[24:25]
	ds_read_b32 v7, v30 offset:32
	ds_read_b32 v9, v30 offset:164
	ds_read_b32 v11, v30 offset:296
	ds_read_b32 v13, v30 offset:428
	v_mov_b32_e32 v24, v3
	s_waitcnt lgkmcnt(0)
	v_mul_f32_e32 v7, 0x43000000, v7
	v_mul_f32_e32 v9, 0x43000000, v9
	v_med3_f32 v7, v7, s20, v46
	v_med3_f32 v9, v9, s20, v46
	v_cvt_pk_fp8_f32 v24, v7, v9
	v_mul_f32_e32 v11, 0x43000000, v11
	v_mul_f32_e32 v13, 0x43000000, v13
	v_med3_f32 v7, v11, s20, v46
	v_med3_f32 v9, v13, s20, v46
	v_cvt_pk_fp8_f32 v24, v7, v9 op_sel:[0,0,1]
	ds_read_b32 v7, v30 offset:560
	ds_read_b32 v9, v30 offset:692
	ds_read_b32 v11, v30 offset:824
	ds_read_b32 v13, v30 offset:956
	v_mov_b32_e32 v25, v3
	s_waitcnt lgkmcnt(0)
	v_mul_f32_e32 v7, 0x43000000, v7
	v_mul_f32_e32 v9, 0x43000000, v9
	v_med3_f32 v7, v7, s20, v46
	v_med3_f32 v9, v9, s20, v46
	v_cvt_pk_fp8_f32 v25, v7, v9
	v_mul_f32_e32 v11, 0x43000000, v11
	v_mul_f32_e32 v13, 0x43000000, v13
	v_med3_f32 v7, v11, s20, v46
	v_med3_f32 v9, v13, s20, v46
	v_cvt_pk_fp8_f32 v25, v7, v9 op_sel:[0,0,1]
	v_or_b32_e32 v48, s8, v27
	v_ashrrev_i32_e32 v49, 31, v48
	v_lshlrev_b64 v[48:49], 10, v[48:49]
	v_lshl_add_u64 v[48:49], v[22:23], 0, v[48:49]
	flat_store_dwordx2 v[48:49], v[24:25]
	ds_read_b32 v7, v30 offset:64
	ds_read_b32 v9, v30 offset:196
	ds_read_b32 v11, v30 offset:328
	ds_read_b32 v13, v30 offset:460
	v_mov_b32_e32 v24, v3
	s_waitcnt lgkmcnt(0)
	v_mul_f32_e32 v7, 0x43000000, v7
	v_mul_f32_e32 v9, 0x43000000, v9
	v_med3_f32 v7, v7, s20, v46
	v_med3_f32 v9, v9, s20, v46
	v_cvt_pk_fp8_f32 v24, v7, v9
	v_mul_f32_e32 v11, 0x43000000, v11
	v_mul_f32_e32 v13, 0x43000000, v13
	v_med3_f32 v7, v11, s20, v46
	v_med3_f32 v9, v13, s20, v46
	v_cvt_pk_fp8_f32 v24, v7, v9 op_sel:[0,0,1]
	ds_read_b32 v7, v30 offset:592
	ds_read_b32 v9, v30 offset:724
	ds_read_b32 v11, v30 offset:856
	ds_read_b32 v13, v30 offset:988
	v_mov_b32_e32 v25, v3
	s_waitcnt lgkmcnt(0)
	v_mul_f32_e32 v7, 0x43000000, v7
	v_mul_f32_e32 v9, 0x43000000, v9
	v_med3_f32 v7, v7, s20, v46
	v_med3_f32 v9, v9, s20, v46
	v_cvt_pk_fp8_f32 v25, v7, v9
	v_mul_f32_e32 v11, 0x43000000, v11
	v_mul_f32_e32 v13, 0x43000000, v13
	v_med3_f32 v7, v11, s20, v46
	v_med3_f32 v9, v13, s20, v46
	v_cvt_pk_fp8_f32 v25, v7, v9 op_sel:[0,0,1]
	v_or_b32_e32 v48, s8, v28
	v_ashrrev_i32_e32 v49, 31, v48
	v_lshlrev_b64 v[48:49], 10, v[48:49]
	v_lshl_add_u64 v[48:49], v[22:23], 0, v[48:49]
	flat_store_dwordx2 v[48:49], v[24:25]
	ds_read_b32 v7, v30 offset:96
	ds_read_b32 v9, v30 offset:228
	ds_read_b32 v11, v30 offset:360
	ds_read_b32 v13, v30 offset:492
	v_mov_b32_e32 v24, v3
	s_waitcnt lgkmcnt(0)
	v_mul_f32_e32 v7, 0x43000000, v7
	v_mul_f32_e32 v9, 0x43000000, v9
	v_med3_f32 v7, v7, s20, v46
	v_med3_f32 v9, v9, s20, v46
	v_cvt_pk_fp8_f32 v24, v7, v9
	v_mul_f32_e32 v11, 0x43000000, v11
	v_mul_f32_e32 v13, 0x43000000, v13
	v_med3_f32 v7, v11, s20, v46
	v_med3_f32 v9, v13, s20, v46
	v_cvt_pk_fp8_f32 v24, v7, v9 op_sel:[0,0,1]
	ds_read_b32 v7, v30 offset:624
	ds_read_b32 v9, v30 offset:756
	ds_read_b32 v11, v30 offset:888
	ds_read_b32 v13, v30 offset:1020
	v_mov_b32_e32 v25, v3
	s_waitcnt lgkmcnt(0)
	v_mul_f32_e32 v7, 0x43000000, v7
	v_mul_f32_e32 v9, 0x43000000, v9
	v_med3_f32 v7, v7, s20, v46
	v_med3_f32 v9, v9, s20, v46
	v_cvt_pk_fp8_f32 v25, v7, v9
	v_mul_f32_e32 v11, 0x43000000, v11
	v_mul_f32_e32 v13, 0x43000000, v13
	v_med3_f32 v7, v11, s20, v46
	v_med3_f32 v9, v13, s20, v46
	v_cvt_pk_fp8_f32 v25, v7, v9 op_sel:[0,0,1]
	v_or_b32_e32 v48, s8, v29
	v_ashrrev_i32_e32 v49, 31, v48
	v_lshlrev_b64 v[48:49], 10, v[48:49]
	v_lshl_add_u64 v[22:23], v[22:23], 0, v[48:49]
	flat_store_dwordx2 v[22:23], v[24:25]
	s_waitcnt lgkmcnt(0)
	s_cbranch_execnz .LBB0_829
	s_branch .LBB0_833

.LBB0_833:
	s_sext_i32_i16 s0, s25
	s_lshr_b32 s0, s0, 9
	s_addk_i32 s24, 0x1ff
	s_cmpk_lt_u32 s24, 0x3ff
	s_cselect_b32 s9, s13, s15
	s_cselect_b32 s19, s12, s14
	s_ashr_i32 s17, s16, 31
	s_sext_i32_i16 s18, s0
	s_lshl_b64 s[0:1], s[16:17], 22
	s_add_u32 s19, s19, s0
	s_addc_u32 s24, s9, s1
	s_lshl_b64 s[0:1], s[16:17], 21
	s_add_u32 s16, s4, s0
	s_addc_u32 s17, s5, s1
	s_ashr_i32 s9, s8, 31
	s_lshl_b64 s[0:1], s[8:9], 2
	s_add_u32 s0, s19, s0
	s_addc_u32 s1, s24, s1
	v_lshl_add_u64 v[22:23], s[0:1], 0, v[2:3]
	s_mov_b64 s[0:1], 0x4000000
	v_lshl_add_u64 v[24:25], v[22:23], 0, s[0:1]
	v_lshlrev_b64 v[20:21], 12, v[20:21]
	v_lshl_add_u64 v[20:21], v[24:25], 0, v[20:21]
	v_ashrrev_i32_e32 v19, 31, v18
	global_load_dwordx4 v[20:23], v[20:21], off nt
	v_lshlrev_b64 v[18:19], 12, v[18:19]
	v_lshl_add_u64 v[18:19], v[24:25], 0, v[18:19]
	v_ashrrev_i32_e32 v17, 31, v16
	global_load_dwordx4 v[48:51], v[18:19], off nt
	v_lshlrev_b64 v[16:17], 12, v[16:17]
	v_lshl_add_u64 v[16:17], v[24:25], 0, v[16:17]
	v_ashrrev_i32_e32 v15, 31, v14
	global_load_dwordx4 v[16:19], v[16:17], off nt
	v_lshlrev_b64 v[14:15], 12, v[14:15]
	v_lshl_add_u64 v[14:15], v[24:25], 0, v[14:15]
	v_ashrrev_i32_e32 v13, 31, v12
	global_load_dwordx4 v[52:55], v[14:15], off nt
	v_lshlrev_b64 v[12:13], 12, v[12:13]
	v_lshl_add_u64 v[12:13], v[24:25], 0, v[12:13]
	v_ashrrev_i32_e32 v11, 31, v10
	global_load_dwordx4 v[12:15], v[12:13], off nt
	v_lshlrev_b64 v[10:11], 12, v[10:11]
	v_lshl_add_u64 v[10:11], v[24:25], 0, v[10:11]
	v_ashrrev_i32_e32 v9, 31, v8
	global_load_dwordx4 v[56:59], v[10:11], off nt
	v_lshlrev_b64 v[8:9], 12, v[8:9]
	v_lshl_add_u64 v[8:9], v[24:25], 0, v[8:9]
	v_ashrrev_i32_e32 v7, 31, v6
	global_load_dwordx4 v[8:11], v[8:9], off nt
	v_lshlrev_b64 v[6:7], 12, v[6:7]
	v_lshl_add_u64 v[6:7], v[24:25], 0, v[6:7]
	global_load_dwordx4 v[60:63], v[6:7], off nt
	s_lshl_b32 s1, s18, 7
	s_ashr_i32 s0, s23, 31
	s_add_u32 s16, s16, s23
	s_addc_u32 s17, s17, s0
	s_lshl_b32 s0, s22, 6
	s_and_b32 s0, s0, 0xffffff00
	s_add_i32 s0, s0, s1
	s_and_b32 s1, s8, 0x60
	s_or_b32 s8, s0, s1
	v_lshl_add_u64 v[6:7], s[16:17], 0, v[4:5]
	s_waitcnt vmcnt(0)
	ds_write2_b32 v31, v20, v21 offset1:1
	ds_write2_b32 v31, v22, v23 offset0:2 offset1:3
	ds_write2_b32 v32, v48, v49 offset1:1
	ds_write2_b32 v33, v50, v51 offset1:1
	ds_write2_b32 v34, v16, v17 offset1:1
	ds_write2_b32 v35, v18, v19 offset1:1
	ds_write2_b32 v36, v52, v53 offset1:1
	ds_write2_b32 v37, v54, v55 offset1:1
	ds_write2_b32 v38, v12, v13 offset1:1
	ds_write2_b32 v39, v14, v15 offset1:1
	ds_write2_b32 v40, v56, v57 offset1:1
	ds_write2_b32 v41, v58, v59 offset1:1
	ds_write2_b32 v42, v8, v9 offset1:1
	ds_write2_b32 v43, v10, v11 offset1:1
	ds_write2_b32 v44, v60, v61 offset1:1
	ds_write2_b32 v45, v62, v63 offset1:1
	s_waitcnt lgkmcnt(0)
	ds_read_b32 v8, v30
	ds_read_b32 v9, v30 offset:132
	ds_read_b32 v10, v30 offset:264
	ds_read_b32 v11, v30 offset:396
	s_waitcnt lgkmcnt(0)
	v_mul_f32_e32 v8, 0x42800000, v8
	v_mul_f32_e32 v9, 0x42800000, v9
	v_med3_f32 v12, v8, s20, v46
	v_med3_f32 v9, v9, s20, v46
	v_mov_b32_e32 v8, v3
	v_cvt_pk_fp8_f32 v8, v12, v9
	v_mul_f32_e32 v10, 0x42800000, v10
	v_mul_f32_e32 v11, 0x42800000, v11
	v_med3_f32 v9, v10, s20, v46
	v_med3_f32 v10, v11, s20, v46
	v_cvt_pk_fp8_f32 v8, v9, v10 op_sel:[0,0,1]
	ds_read_b32 v9, v30 offset:528
	ds_read_b32 v10, v30 offset:660
	ds_read_b32 v11, v30 offset:792
	ds_read_b32 v12, v30 offset:924
	s_waitcnt lgkmcnt(3)
	v_mul_f32_e32 v9, 0x42800000, v9
	s_waitcnt lgkmcnt(2)
	v_mul_f32_e32 v10, 0x42800000, v10
	v_med3_f32 v13, v9, s20, v46
	v_med3_f32 v10, v10, s20, v46
	v_mov_b32_e32 v9, v3
	v_cvt_pk_fp8_f32 v9, v13, v10
	s_waitcnt lgkmcnt(1)
	v_mul_f32_e32 v11, 0x42800000, v11
	s_waitcnt lgkmcnt(0)
	v_mul_f32_e32 v12, 0x42800000, v12
	v_med3_f32 v10, v11, s20, v46
	v_med3_f32 v11, v12, s20, v46
	v_cvt_pk_fp8_f32 v9, v10, v11 op_sel:[0,0,1]
	v_or_b32_e32 v10, s8, v26
	v_ashrrev_i32_e32 v11, 31, v10
	v_lshlrev_b64 v[10:11], 10, v[10:11]
	v_lshl_add_u64 v[10:11], v[6:7], 0, v[10:11]
	flat_store_dwordx2 v[10:11], v[8:9]
	ds_read_b32 v8, v30 offset:32
	ds_read_b32 v9, v30 offset:164
	ds_read_b32 v10, v30 offset:296
	ds_read_b32 v11, v30 offset:428
	s_waitcnt lgkmcnt(0)
	v_mul_f32_e32 v8, 0x42800000, v8
	v_mul_f32_e32 v9, 0x42800000, v9
	v_med3_f32 v12, v8, s20, v46
	v_med3_f32 v9, v9, s20, v46
	v_mov_b32_e32 v8, v3
	v_cvt_pk_fp8_f32 v8, v12, v9
	v_mul_f32_e32 v10, 0x42800000, v10
	v_mul_f32_e32 v11, 0x42800000, v11
	v_med3_f32 v9, v10, s20, v46
	v_med3_f32 v10, v11, s20, v46
	v_cvt_pk_fp8_f32 v8, v9, v10 op_sel:[0,0,1]
	ds_read_b32 v9, v30 offset:560
	ds_read_b32 v10, v30 offset:692
	ds_read_b32 v11, v30 offset:824
	ds_read_b32 v12, v30 offset:956
	s_waitcnt lgkmcnt(0)
	v_mul_f32_e32 v9, 0x42800000, v9
	v_mul_f32_e32 v10, 0x42800000, v10
	v_med3_f32 v13, v9, s20, v46
	v_med3_f32 v10, v10, s20, v46
	v_mov_b32_e32 v9, v3
	v_cvt_pk_fp8_f32 v9, v13, v10
	v_mul_f32_e32 v11, 0x42800000, v11
	v_mul_f32_e32 v12, 0x42800000, v12
	v_med3_f32 v10, v11, s20, v46
	v_med3_f32 v11, v12, s20, v46
	v_cvt_pk_fp8_f32 v9, v10, v11 op_sel:[0,0,1]
	v_or_b32_e32 v10, s8, v27
	v_ashrrev_i32_e32 v11, 31, v10
	v_lshlrev_b64 v[10:11], 10, v[10:11]
	v_lshl_add_u64 v[10:11], v[6:7], 0, v[10:11]
	flat_store_dwordx2 v[10:11], v[8:9]
	ds_read_b32 v8, v30 offset:64
	ds_read_b32 v9, v30 offset:196
	ds_read_b32 v10, v30 offset:328
	ds_read_b32 v11, v30 offset:460
	s_waitcnt lgkmcnt(0)
	v_mul_f32_e32 v8, 0x42800000, v8
	v_mul_f32_e32 v9, 0x42800000, v9
	v_med3_f32 v12, v8, s20, v46
	v_med3_f32 v9, v9, s20, v46
	v_mov_b32_e32 v8, v3
	v_cvt_pk_fp8_f32 v8, v12, v9
	v_mul_f32_e32 v10, 0x42800000, v10
	v_mul_f32_e32 v11, 0x42800000, v11
	v_med3_f32 v9, v10, s20, v46
	v_med3_f32 v10, v11, s20, v46
	v_cvt_pk_fp8_f32 v8, v9, v10 op_sel:[0,0,1]
	ds_read_b32 v9, v30 offset:592
	ds_read_b32 v10, v30 offset:724
	ds_read_b32 v11, v30 offset:856
	ds_read_b32 v12, v30 offset:988
	s_waitcnt lgkmcnt(0)
	v_mul_f32_e32 v9, 0x42800000, v9
	v_mul_f32_e32 v10, 0x42800000, v10
	v_med3_f32 v13, v9, s20, v46
	v_med3_f32 v10, v10, s20, v46
	v_mov_b32_e32 v9, v3
	v_cvt_pk_fp8_f32 v9, v13, v10
	v_mul_f32_e32 v11, 0x42800000, v11
	v_mul_f32_e32 v12, 0x42800000, v12
	v_med3_f32 v10, v11, s20, v46
	v_med3_f32 v11, v12, s20, v46
	v_cvt_pk_fp8_f32 v9, v10, v11 op_sel:[0,0,1]
	v_or_b32_e32 v10, s8, v28
	v_ashrrev_i32_e32 v11, 31, v10
	v_lshlrev_b64 v[10:11], 10, v[10:11]
	v_lshl_add_u64 v[10:11], v[6:7], 0, v[10:11]
	flat_store_dwordx2 v[10:11], v[8:9]
	ds_read_b32 v8, v30 offset:96
	ds_read_b32 v9, v30 offset:228
	ds_read_b32 v10, v30 offset:360
	ds_read_b32 v11, v30 offset:492
	s_waitcnt lgkmcnt(0)
	v_mul_f32_e32 v8, 0x42800000, v8
	v_mul_f32_e32 v9, 0x42800000, v9
	v_med3_f32 v12, v8, s20, v46
	v_med3_f32 v9, v9, s20, v46
	v_mov_b32_e32 v8, v3
	v_cvt_pk_fp8_f32 v8, v12, v9
	v_mul_f32_e32 v10, 0x42800000, v10
	v_mul_f32_e32 v11, 0x42800000, v11
	v_med3_f32 v9, v10, s20, v46
	v_med3_f32 v10, v11, s20, v46
	v_cvt_pk_fp8_f32 v8, v9, v10 op_sel:[0,0,1]
	ds_read_b32 v9, v30 offset:624
	ds_read_b32 v10, v30 offset:756
	ds_read_b32 v11, v30 offset:888
	ds_read_b32 v12, v30 offset:1020
	s_waitcnt lgkmcnt(0)
	v_mul_f32_e32 v9, 0x42800000, v9
	v_mul_f32_e32 v10, 0x42800000, v10
	v_med3_f32 v13, v9, s20, v46
	v_med3_f32 v10, v10, s20, v46
	v_mov_b32_e32 v9, v3
	v_cvt_pk_fp8_f32 v9, v13, v10
	v_mul_f32_e32 v11, 0x42800000, v11
	v_mul_f32_e32 v12, 0x42800000, v12
	v_med3_f32 v10, v11, s20, v46
	v_med3_f32 v11, v12, s20, v46
	v_cvt_pk_fp8_f32 v9, v10, v11 op_sel:[0,0,1]
	v_or_b32_e32 v10, s8, v29
	v_ashrrev_i32_e32 v11, 31, v10
	v_lshlrev_b64 v[10:11], 10, v[10:11]
	v_lshl_add_u64 v[6:7], v[6:7], 0, v[10:11]
	flat_store_dwordx2 v[6:7], v[8:9]
	s_waitcnt lgkmcnt(0)
	s_branch .LBB0_829

.LBB0_1427:
	s_or_b64 exec, exec, s[8:9]
	s_waitcnt lgkmcnt(0)
	s_barrier
	s_load_dwordx4 s[4:7], s[84:85], 0xf8
	s_load_dwordx2 s[24:25], s[84:85], 0x108
	s_load_dwordx8 s[16:23], s[84:85], 0xd8
	v_mov_b32_e32 v39, v0
	s_waitcnt lgkmcnt(0)
	s_mov_b32 s0, s7
	v_and_b32_e32 v74, 63, v39
	s_mov_b32 s8, s25
	s_add_u32 s26, s24, 0x3e00000
	v_lshlrev_b32_e32 v34, 4, v74
	v_mov_b32_e32 v35, 0
	s_addc_u32 s27, s8, 0
	v_lshl_add_u64 v[2:3], s[22:23], 0, v[34:35]
	s_mov_b64 s[0:1], 0x3000
	v_lshl_add_u64 v[6:7], s[4:5], 0, v[34:35]
	v_lshl_add_u64 v[26:27], v[2:3], 0, s[0:1]
	v_lshl_add_u64 v[30:31], v[6:7], 0, s[0:1]
	s_movk_i32 s0, 0x3000
	s_add_u32 s22, s24, 0x3900000
	v_add_co_u32_e32 v2, vcc, s0, v2
	s_addc_u32 s23, s8, 0
	s_nop 0
	v_addc_co_u32_e32 v3, vcc, 0, v3, vcc
	s_add_u32 s14, s24, 0xa100000
	v_add_co_u32_e32 v6, vcc, s0, v6
	s_addc_u32 s15, s8, 0
	v_readlane_b32 s0, v253, 36
	v_readlane_b32 s1, v253, 37
	s_add_u32 s0, s14, s0
	s_addc_u32 s1, s15, s1
	v_readlane_b32 s4, v253, 38
	v_readlane_b32 s5, v253, 39
	s_add_u32 s4, s14, s4
	v_lshlrev_b32_e32 v34, 3, v74
	v_addc_co_u32_e32 v7, vcc, 0, v7, vcc
	s_addc_u32 s5, s15, s5
	v_lshl_add_u64 v[36:37], s[0:1], 0, v[34:35]
	global_load_dwordx4 v[2:5], v[2:3], off nt
	s_nop 0
	global_load_dwordx4 v[6:9], v[6:7], off nt
	s_nop 0
	global_load_dwordx4 v[10:13], v[26:27], off offset:1024
	global_load_dwordx4 v[14:17], v[26:27], off offset:2048
	global_load_dwordx4 v[18:21], v[30:31], off offset:1024
	global_load_dwordx4 v[22:25], v[30:31], off offset:2048
	s_nop 0
	global_load_dwordx4 v[26:29], v[26:27], off offset:3072
	s_nop 0
	global_load_dwordx4 v[30:33], v[30:31], off offset:3072
	v_lshl_add_u64 v[46:47], s[4:5], 0, v[34:35]
	flat_load_dwordx2 v[64:65], v[36:37]
	flat_load_dwordx2 v[62:63], v[36:37] offset:512
	flat_load_dwordx2 v[60:61], v[36:37] offset:1024
	flat_load_dwordx2 v[58:59], v[36:37] offset:1536
	flat_load_dwordx2 v[44:45], v[46:47]
	flat_load_dwordx2 v[42:43], v[46:47] offset:512
	flat_load_dwordx2 v[40:41], v[46:47] offset:1024
	s_nop 0
	flat_load_dwordx2 v[36:37], v[46:47] offset:1536
	s_mov_b32 s7, s8
	v_cmp_gt_u32_e64 s[12:13], 16, v74
	v_mov_b32_e32 v75, -1
	v_lshlrev_b32_e32 v38, 11, v74
	v_mov_b32_e32 v82, v35
	v_mov_b32_e32 v81, -1
	s_and_saveexec_b64 s[8:9], s[12:13]
	s_cbranch_execz .LBB0_1429
	v_readlane_b32 s0, v253, 34
	v_readlane_b32 s1, v253, 35
	s_mov_b32 s4, s0
	s_ashr_i32 s0, s0, 11
	s_ashr_i32 s1, s0, 31
	s_lshl_b64 s[0:1], s[0:1], 15
	s_and_b32 s4, s4, 0x7ff
	s_or_b32 s0, s0, s4
	s_ashr_i32 s4, s68, 11
	s_ashr_i32 s5, s4, 31
	s_lshl_b64 s[4:5], s[4:5], 15
	s_and_b32 s6, s68, 0x7ff
	s_or_b32 s4, s4, s6
	v_or_b32_e32 v46, s4, v38
	v_mov_b32_e32 v47, s5
	v_lshl_add_u64 v[48:49], v[46:47], 1, s[26:27]
	v_lshl_add_u64 v[46:47], v[46:47], 2, s[22:23]
	flat_load_sshort v81, v[48:49]
	flat_load_dword v82, v[46:47]
	v_or_b32_e32 v46, s0, v38
	v_mov_b32_e32 v47, s1
	v_lshl_add_u64 v[48:49], v[46:47], 1, s[26:27]
	v_lshl_add_u64 v[46:47], v[46:47], 2, s[22:23]
	flat_load_sshort v75, v[48:49]
	flat_load_dword v35, v[46:47]

.LBB0_1444:
	s_mul_hi_i32 s0, s11, 0x2aaaaaab
	s_lshr_b32 s1, s0, 31
	s_ashr_i32 s0, s0, 8
	s_add_i32 s14, s0, s1
	s_mul_i32 s0, s14, 0xfffffa00
	s_add_i32 s24, s11, s0
	s_lshr_b32 s0, s24, 22
	s_and_b32 s0, s0, 0x1ff
	s_add_i32 s25, s24, s0
	s_and_b32 s0, s25, 0xfe00
	s_sub_i32 s0, s24, s0
	s_sext_i32_i16 s1, s0
	s_bfe_u32 s1, s1, 0x5001a
	s_add_i32 s1, s0, s1
	s_sext_i32_i16 s12, s1
	s_and_b32 s1, s1, 0xffe0
	s_lshl_b32 s23, s12, 1
	s_sub_i32 s0, s0, s1
	s_andn2_b32 s23, s23, 63
	s_sext_i32_i16 s22, s0
	s_lshl_b32 s12, s22, 5
	v_or_b32_e32 v20, s23, v26
	s_mov_b64 s[20:21], -1
	s_cmpk_gt_i32 s24, 0x3ff
	v_ashrrev_i32_e32 v21, 31, v20
	v_or_b32_e32 v18, 8, v20
	v_or_b32_e32 v16, 16, v20
	v_or_b32_e32 v14, 24, v20
	v_or_b32_e32 v12, 32, v20
	v_or_b32_e32 v10, 40, v20
	v_or_b32_e32 v8, 48, v20
	v_or_b32_e32 v6, 56, v20
	s_cbranch_scc0 .LBB0_1446
	s_ashr_i32 s15, s14, 31
	s_lshl_b64 s[0:1], s[14:15], 20
	s_lshl_b64 s[20:21], s[14:15], 22
	s_add_u32 s15, s8, s20
	s_addc_u32 s20, s9, s21
	s_add_u32 s21, s6, s0
	s_addc_u32 s26, s7, s1
	s_ashr_i32 s13, s12, 31
	s_lshl_b64 s[0:1], s[12:13], 2
	s_add_u32 s0, s15, s0
	s_addc_u32 s1, s20, s1
	v_lshl_add_u64 v[72:73], s[0:1], 0, v[2:3]
	v_lshlrev_b64 v[22:23], 12, v[20:21]
	v_lshl_add_u64 v[22:23], v[72:73], 0, v[22:23]
	v_ashrrev_i32_e32 v19, 31, v18
	global_load_dwordx4 v[22:25], v[22:23], off nt
	v_lshlrev_b64 v[48:49], 12, v[18:19]
	v_lshl_add_u64 v[48:49], v[72:73], 0, v[48:49]
	v_ashrrev_i32_e32 v17, 31, v16
	global_load_dwordx4 v[48:51], v[48:49], off nt
	v_lshlrev_b64 v[52:53], 12, v[16:17]
	v_lshl_add_u64 v[52:53], v[72:73], 0, v[52:53]
	v_ashrrev_i32_e32 v15, 31, v14
	global_load_dwordx4 v[52:55], v[52:53], off nt
	v_lshlrev_b64 v[56:57], 12, v[14:15]
	v_lshl_add_u64 v[56:57], v[72:73], 0, v[56:57]
	v_ashrrev_i32_e32 v13, 31, v12
	global_load_dwordx4 v[56:59], v[56:57], off nt
	v_lshlrev_b64 v[60:61], 12, v[12:13]
	v_lshl_add_u64 v[60:61], v[72:73], 0, v[60:61]
	v_ashrrev_i32_e32 v11, 31, v10
	global_load_dwordx4 v[60:63], v[60:61], off nt
	v_lshlrev_b64 v[64:65], 12, v[10:11]
	v_lshl_add_u64 v[64:65], v[72:73], 0, v[64:65]
	v_ashrrev_i32_e32 v9, 31, v8
	global_load_dwordx4 v[64:67], v[64:65], off nt
	v_lshlrev_b64 v[68:69], 12, v[8:9]
	v_lshl_add_u64 v[68:69], v[72:73], 0, v[68:69]
	v_ashrrev_i32_e32 v7, 31, v6
	global_load_dwordx4 v[68:71], v[68:69], off nt
	v_lshlrev_b64 v[74:75], 12, v[6:7]
	v_lshl_add_u64 v[72:73], v[72:73], 0, v[74:75]
	global_load_dwordx4 v[72:75], v[72:73], off nt
	s_ashr_i32 s1, s23, 31
	s_add_u32 s0, s21, s23
	s_addc_u32 s1, s26, s1
	s_waitcnt vmcnt(0)
	ds_write2_b32 v31, v22, v23 offset1:1
	ds_write2_b32 v31, v24, v25 offset0:2 offset1:3
	s_waitcnt vmcnt(6)
	ds_write2_b32 v32, v48, v49 offset1:1
	ds_write2_b32 v33, v50, v51 offset1:1
	s_waitcnt vmcnt(5)
	ds_write2_b32 v34, v52, v53 offset1:1
	ds_write2_b32 v35, v54, v55 offset1:1
	s_waitcnt vmcnt(4)
	ds_write2_b32 v36, v56, v57 offset1:1
	ds_write2_b32 v37, v58, v59 offset1:1
	s_waitcnt vmcnt(3)
	ds_write2_b32 v38, v60, v61 offset1:1
	ds_write2_b32 v39, v62, v63 offset1:1
	s_waitcnt vmcnt(2)
	ds_write2_b32 v40, v64, v65 offset1:1
	ds_write2_b32 v41, v66, v67 offset1:1
	s_waitcnt vmcnt(1)
	ds_write2_b32 v42, v68, v69 offset1:1
	ds_write2_b32 v43, v70, v71 offset1:1
	s_waitcnt vmcnt(0)
	ds_write2_b32 v44, v72, v73 offset1:1
	ds_write2_b32 v45, v74, v75 offset1:1
	s_waitcnt lgkmcnt(0)
	ds_read_b32 v7, v30
	ds_read_b32 v9, v30 offset:132
	ds_read_b32 v11, v30 offset:264
	ds_read_b32 v13, v30 offset:396
	v_mov_b32_e32 v24, v3
	s_waitcnt lgkmcnt(0)
	v_mul_f32_e32 v7, 0x43000000, v7
	s_waitcnt lgkmcnt(2)
	v_mul_f32_e32 v9, 0x43000000, v9
	v_med3_f32 v7, v7, s10, v46
	v_med3_f32 v9, v9, s10, v46
	v_cvt_pk_fp8_f32 v24, v7, v9
	s_waitcnt lgkmcnt(1)
	v_mul_f32_e32 v11, 0x43000000, v11
	s_waitcnt lgkmcnt(0)
	v_mul_f32_e32 v13, 0x43000000, v13
	v_med3_f32 v7, v11, s10, v46
	v_med3_f32 v9, v13, s10, v46
	v_cvt_pk_fp8_f32 v24, v7, v9 op_sel:[0,0,1]
	ds_read_b32 v7, v30 offset:528
	ds_read_b32 v9, v30 offset:660
	ds_read_b32 v11, v30 offset:792
	ds_read_b32 v13, v30 offset:924
	v_mov_b32_e32 v25, v3
	s_waitcnt lgkmcnt(3)
	v_mul_f32_e32 v7, 0x43000000, v7
	s_waitcnt lgkmcnt(2)
	v_mul_f32_e32 v9, 0x43000000, v9
	v_med3_f32 v7, v7, s10, v46
	v_med3_f32 v9, v9, s10, v46
	v_cvt_pk_fp8_f32 v25, v7, v9
	s_waitcnt lgkmcnt(1)
	v_mul_f32_e32 v11, 0x43000000, v11
	s_waitcnt lgkmcnt(0)
	v_mul_f32_e32 v13, 0x43000000, v13
	v_med3_f32 v7, v11, s10, v46
	v_med3_f32 v9, v13, s10, v46
	v_cvt_pk_fp8_f32 v25, v7, v9 op_sel:[0,0,1]
	v_or_b32_e32 v48, s12, v26
	v_ashrrev_i32_e32 v49, 31, v48
	v_lshl_add_u64 v[22:23], s[0:1], 0, v[4:5]
	v_lshlrev_b64 v[48:49], 10, v[48:49]
	v_lshl_add_u64 v[48:49], v[22:23], 0, v[48:49]
	flat_store_dwordx2 v[48:49], v[24:25]
	ds_read_b32 v7, v30 offset:32
	ds_read_b32 v9, v30 offset:164
	ds_read_b32 v11, v30 offset:296
	ds_read_b32 v13, v30 offset:428
	v_mov_b32_e32 v24, v3
	s_waitcnt lgkmcnt(0)
	v_mul_f32_e32 v7, 0x43000000, v7
	v_mul_f32_e32 v9, 0x43000000, v9
	v_med3_f32 v7, v7, s10, v46
	v_med3_f32 v9, v9, s10, v46
	v_cvt_pk_fp8_f32 v24, v7, v9
	v_mul_f32_e32 v11, 0x43000000, v11
	v_mul_f32_e32 v13, 0x43000000, v13
	v_med3_f32 v7, v11, s10, v46
	v_med3_f32 v9, v13, s10, v46
	v_cvt_pk_fp8_f32 v24, v7, v9 op_sel:[0,0,1]
	ds_read_b32 v7, v30 offset:560
	ds_read_b32 v9, v30 offset:692
	ds_read_b32 v11, v30 offset:824
	ds_read_b32 v13, v30 offset:956
	v_mov_b32_e32 v25, v3
	s_waitcnt lgkmcnt(0)
	v_mul_f32_e32 v7, 0x43000000, v7
	v_mul_f32_e32 v9, 0x43000000, v9
	v_med3_f32 v7, v7, s10, v46
	v_med3_f32 v9, v9, s10, v46
	v_cvt_pk_fp8_f32 v25, v7, v9
	v_mul_f32_e32 v11, 0x43000000, v11
	v_mul_f32_e32 v13, 0x43000000, v13
	v_med3_f32 v7, v11, s10, v46
	v_med3_f32 v9, v13, s10, v46
	v_cvt_pk_fp8_f32 v25, v7, v9 op_sel:[0,0,1]
	v_or_b32_e32 v48, s12, v27
	v_ashrrev_i32_e32 v49, 31, v48
	v_lshlrev_b64 v[48:49], 10, v[48:49]
	v_lshl_add_u64 v[48:49], v[22:23], 0, v[48:49]
	flat_store_dwordx2 v[48:49], v[24:25]
	ds_read_b32 v7, v30 offset:64
	ds_read_b32 v9, v30 offset:196
	ds_read_b32 v11, v30 offset:328
	ds_read_b32 v13, v30 offset:460
	v_mov_b32_e32 v24, v3
	s_waitcnt lgkmcnt(0)
	v_mul_f32_e32 v7, 0x43000000, v7
	v_mul_f32_e32 v9, 0x43000000, v9
	v_med3_f32 v7, v7, s10, v46
	v_med3_f32 v9, v9, s10, v46
	v_cvt_pk_fp8_f32 v24, v7, v9
	v_mul_f32_e32 v11, 0x43000000, v11
	v_mul_f32_e32 v13, 0x43000000, v13
	v_med3_f32 v7, v11, s10, v46
	v_med3_f32 v9, v13, s10, v46
	v_cvt_pk_fp8_f32 v24, v7, v9 op_sel:[0,0,1]
	ds_read_b32 v7, v30 offset:592
	ds_read_b32 v9, v30 offset:724
	ds_read_b32 v11, v30 offset:856
	ds_read_b32 v13, v30 offset:988
	v_mov_b32_e32 v25, v3
	s_waitcnt lgkmcnt(0)
	v_mul_f32_e32 v7, 0x43000000, v7
	v_mul_f32_e32 v9, 0x43000000, v9
	v_med3_f32 v7, v7, s10, v46
	v_med3_f32 v9, v9, s10, v46
	v_cvt_pk_fp8_f32 v25, v7, v9
	v_mul_f32_e32 v11, 0x43000000, v11
	v_mul_f32_e32 v13, 0x43000000, v13
	v_med3_f32 v7, v11, s10, v46
	v_med3_f32 v9, v13, s10, v46
	v_cvt_pk_fp8_f32 v25, v7, v9 op_sel:[0,0,1]
	v_or_b32_e32 v48, s12, v28
	v_ashrrev_i32_e32 v49, 31, v48
	v_lshlrev_b64 v[48:49], 10, v[48:49]
	v_lshl_add_u64 v[48:49], v[22:23], 0, v[48:49]
	flat_store_dwordx2 v[48:49], v[24:25]
	ds_read_b32 v7, v30 offset:96
	ds_read_b32 v9, v30 offset:228
	ds_read_b32 v11, v30 offset:360
	ds_read_b32 v13, v30 offset:492
	v_mov_b32_e32 v24, v3
	s_waitcnt lgkmcnt(0)
	v_mul_f32_e32 v7, 0x43000000, v7
	v_mul_f32_e32 v9, 0x43000000, v9
	v_med3_f32 v7, v7, s10, v46
	v_med3_f32 v9, v9, s10, v46
	v_cvt_pk_fp8_f32 v24, v7, v9
	v_mul_f32_e32 v11, 0x43000000, v11
	v_mul_f32_e32 v13, 0x43000000, v13
	v_med3_f32 v7, v11, s10, v46
	v_med3_f32 v9, v13, s10, v46
	v_cvt_pk_fp8_f32 v24, v7, v9 op_sel:[0,0,1]
	ds_read_b32 v7, v30 offset:624
	ds_read_b32 v9, v30 offset:756
	ds_read_b32 v11, v30 offset:888
	ds_read_b32 v13, v30 offset:1020
	v_mov_b32_e32 v25, v3
	s_waitcnt lgkmcnt(0)
	v_mul_f32_e32 v7, 0x43000000, v7
	v_mul_f32_e32 v9, 0x43000000, v9
	v_med3_f32 v7, v7, s10, v46
	v_med3_f32 v9, v9, s10, v46
	v_cvt_pk_fp8_f32 v25, v7, v9
	v_mul_f32_e32 v11, 0x43000000, v11
	v_mul_f32_e32 v13, 0x43000000, v13
	v_med3_f32 v7, v11, s10, v46
	v_med3_f32 v9, v13, s10, v46
	v_cvt_pk_fp8_f32 v25, v7, v9 op_sel:[0,0,1]
	v_or_b32_e32 v48, s12, v29
	v_ashrrev_i32_e32 v49, 31, v48
	v_lshlrev_b64 v[48:49], 10, v[48:49]
	v_lshl_add_u64 v[22:23], v[22:23], 0, v[48:49]
	flat_store_dwordx2 v[22:23], v[24:25]
	s_waitcnt lgkmcnt(0)
	s_cbranch_execnz .LBB0_1443
	s_branch .LBB0_1447

.LBB0_1447:
	s_sext_i32_i16 s0, s25
	s_lshr_b32 s0, s0, 9
	s_addk_i32 s24, 0x1ff
	s_cmpk_lt_u32 s24, 0x3ff
	s_cselect_b32 s13, s17, s19
	s_cselect_b32 s21, s16, s18
	s_ashr_i32 s15, s14, 31
	s_sext_i32_i16 s20, s0
	s_lshl_b64 s[0:1], s[14:15], 22
	s_add_u32 s21, s21, s0
	s_addc_u32 s24, s13, s1
	s_lshl_b64 s[0:1], s[14:15], 21
	s_add_u32 s14, s4, s0
	s_addc_u32 s15, s5, s1
	s_ashr_i32 s13, s12, 31
	s_lshl_b64 s[0:1], s[12:13], 2
	s_add_u32 s0, s21, s0
	s_addc_u32 s1, s24, s1
	v_lshl_add_u64 v[22:23], s[0:1], 0, v[2:3]
	s_mov_b64 s[0:1], 0x8000000
	v_lshl_add_u64 v[24:25], v[22:23], 0, s[0:1]
	v_lshlrev_b64 v[20:21], 12, v[20:21]
	v_lshl_add_u64 v[20:21], v[24:25], 0, v[20:21]
	v_ashrrev_i32_e32 v19, 31, v18
	global_load_dwordx4 v[20:23], v[20:21], off nt
	v_lshlrev_b64 v[18:19], 12, v[18:19]
	v_lshl_add_u64 v[18:19], v[24:25], 0, v[18:19]
	v_ashrrev_i32_e32 v17, 31, v16
	global_load_dwordx4 v[48:51], v[18:19], off nt
	v_lshlrev_b64 v[16:17], 12, v[16:17]
	v_lshl_add_u64 v[16:17], v[24:25], 0, v[16:17]
	v_ashrrev_i32_e32 v15, 31, v14
	global_load_dwordx4 v[16:19], v[16:17], off nt
	v_lshlrev_b64 v[14:15], 12, v[14:15]
	v_lshl_add_u64 v[14:15], v[24:25], 0, v[14:15]
	v_ashrrev_i32_e32 v13, 31, v12
	global_load_dwordx4 v[52:55], v[14:15], off nt
	v_lshlrev_b64 v[12:13], 12, v[12:13]
	v_lshl_add_u64 v[12:13], v[24:25], 0, v[12:13]
	v_ashrrev_i32_e32 v11, 31, v10
	global_load_dwordx4 v[12:15], v[12:13], off nt
	v_lshlrev_b64 v[10:11], 12, v[10:11]
	v_lshl_add_u64 v[10:11], v[24:25], 0, v[10:11]
	v_ashrrev_i32_e32 v9, 31, v8
	global_load_dwordx4 v[56:59], v[10:11], off nt
	v_lshlrev_b64 v[8:9], 12, v[8:9]
	v_lshl_add_u64 v[8:9], v[24:25], 0, v[8:9]
	v_ashrrev_i32_e32 v7, 31, v6
	global_load_dwordx4 v[8:11], v[8:9], off nt
	v_lshlrev_b64 v[6:7], 12, v[6:7]
	v_lshl_add_u64 v[6:7], v[24:25], 0, v[6:7]
	global_load_dwordx4 v[60:63], v[6:7], off nt
	s_lshl_b32 s1, s20, 7
	s_ashr_i32 s0, s23, 31
	s_add_u32 s14, s14, s23
	s_addc_u32 s15, s15, s0
	s_lshl_b32 s0, s22, 6
	s_and_b32 s0, s0, 0xffffff00
	s_add_i32 s0, s0, s1
	s_and_b32 s1, s12, 0x60
	s_or_b32 s12, s0, s1
	v_lshl_add_u64 v[6:7], s[14:15], 0, v[4:5]
	s_waitcnt vmcnt(0)
	ds_write2_b32 v31, v20, v21 offset1:1
	ds_write2_b32 v31, v22, v23 offset0:2 offset1:3
	ds_write2_b32 v32, v48, v49 offset1:1
	ds_write2_b32 v33, v50, v51 offset1:1
	ds_write2_b32 v34, v16, v17 offset1:1
	ds_write2_b32 v35, v18, v19 offset1:1
	ds_write2_b32 v36, v52, v53 offset1:1
	ds_write2_b32 v37, v54, v55 offset1:1
	ds_write2_b32 v38, v12, v13 offset1:1
	ds_write2_b32 v39, v14, v15 offset1:1
	ds_write2_b32 v40, v56, v57 offset1:1
	ds_write2_b32 v41, v58, v59 offset1:1
	ds_write2_b32 v42, v8, v9 offset1:1
	ds_write2_b32 v43, v10, v11 offset1:1
	ds_write2_b32 v44, v60, v61 offset1:1
	ds_write2_b32 v45, v62, v63 offset1:1
	s_waitcnt lgkmcnt(0)
	ds_read_b32 v8, v30
	ds_read_b32 v9, v30 offset:132
	ds_read_b32 v10, v30 offset:264
	ds_read_b32 v11, v30 offset:396
	s_waitcnt lgkmcnt(0)
	v_mul_f32_e32 v8, 0x42800000, v8
	v_mul_f32_e32 v9, 0x42800000, v9
	v_med3_f32 v12, v8, s10, v46
	v_med3_f32 v9, v9, s10, v46
	v_mov_b32_e32 v8, v3
	v_cvt_pk_fp8_f32 v8, v12, v9
	v_mul_f32_e32 v10, 0x42800000, v10
	v_mul_f32_e32 v11, 0x42800000, v11
	v_med3_f32 v9, v10, s10, v46
	v_med3_f32 v10, v11, s10, v46
	v_cvt_pk_fp8_f32 v8, v9, v10 op_sel:[0,0,1]
	ds_read_b32 v9, v30 offset:528
	ds_read_b32 v10, v30 offset:660
	ds_read_b32 v11, v30 offset:792
	ds_read_b32 v12, v30 offset:924
	s_waitcnt lgkmcnt(3)
	v_mul_f32_e32 v9, 0x42800000, v9
	s_waitcnt lgkmcnt(2)
	v_mul_f32_e32 v10, 0x42800000, v10
	v_med3_f32 v13, v9, s10, v46
	v_med3_f32 v10, v10, s10, v46
	v_mov_b32_e32 v9, v3
	v_cvt_pk_fp8_f32 v9, v13, v10
	s_waitcnt lgkmcnt(1)
	v_mul_f32_e32 v11, 0x42800000, v11
	s_waitcnt lgkmcnt(0)
	v_mul_f32_e32 v12, 0x42800000, v12
	v_med3_f32 v10, v11, s10, v46
	v_med3_f32 v11, v12, s10, v46
	v_cvt_pk_fp8_f32 v9, v10, v11 op_sel:[0,0,1]
	v_or_b32_e32 v10, s12, v26
	v_ashrrev_i32_e32 v11, 31, v10
	v_lshlrev_b64 v[10:11], 10, v[10:11]
	v_lshl_add_u64 v[10:11], v[6:7], 0, v[10:11]
	flat_store_dwordx2 v[10:11], v[8:9]
	ds_read_b32 v8, v30 offset:32
	ds_read_b32 v9, v30 offset:164
	ds_read_b32 v10, v30 offset:296
	ds_read_b32 v11, v30 offset:428
	s_waitcnt lgkmcnt(0)
	v_mul_f32_e32 v8, 0x42800000, v8
	v_mul_f32_e32 v9, 0x42800000, v9
	v_med3_f32 v12, v8, s10, v46
	v_med3_f32 v9, v9, s10, v46
	v_mov_b32_e32 v8, v3
	v_cvt_pk_fp8_f32 v8, v12, v9
	v_mul_f32_e32 v10, 0x42800000, v10
	v_mul_f32_e32 v11, 0x42800000, v11
	v_med3_f32 v9, v10, s10, v46
	v_med3_f32 v10, v11, s10, v46
	v_cvt_pk_fp8_f32 v8, v9, v10 op_sel:[0,0,1]
	ds_read_b32 v9, v30 offset:560
	ds_read_b32 v10, v30 offset:692
	ds_read_b32 v11, v30 offset:824
	ds_read_b32 v12, v30 offset:956
	s_waitcnt lgkmcnt(0)
	v_mul_f32_e32 v9, 0x42800000, v9
	v_mul_f32_e32 v10, 0x42800000, v10
	v_med3_f32 v13, v9, s10, v46
	v_med3_f32 v10, v10, s10, v46
	v_mov_b32_e32 v9, v3
	v_cvt_pk_fp8_f32 v9, v13, v10
	v_mul_f32_e32 v11, 0x42800000, v11
	v_mul_f32_e32 v12, 0x42800000, v12
	v_med3_f32 v10, v11, s10, v46
	v_med3_f32 v11, v12, s10, v46
	v_cvt_pk_fp8_f32 v9, v10, v11 op_sel:[0,0,1]
	v_or_b32_e32 v10, s12, v27
	v_ashrrev_i32_e32 v11, 31, v10
	v_lshlrev_b64 v[10:11], 10, v[10:11]
	v_lshl_add_u64 v[10:11], v[6:7], 0, v[10:11]
	flat_store_dwordx2 v[10:11], v[8:9]
	ds_read_b32 v8, v30 offset:64
	ds_read_b32 v9, v30 offset:196
	ds_read_b32 v10, v30 offset:328
	ds_read_b32 v11, v30 offset:460
	s_waitcnt lgkmcnt(0)
	v_mul_f32_e32 v8, 0x42800000, v8
	v_mul_f32_e32 v9, 0x42800000, v9
	v_med3_f32 v12, v8, s10, v46
	v_med3_f32 v9, v9, s10, v46
	v_mov_b32_e32 v8, v3
	v_cvt_pk_fp8_f32 v8, v12, v9
	v_mul_f32_e32 v10, 0x42800000, v10
	v_mul_f32_e32 v11, 0x42800000, v11
	v_med3_f32 v9, v10, s10, v46
	v_med3_f32 v10, v11, s10, v46
	v_cvt_pk_fp8_f32 v8, v9, v10 op_sel:[0,0,1]
	ds_read_b32 v9, v30 offset:592
	ds_read_b32 v10, v30 offset:724
	ds_read_b32 v11, v30 offset:856
	ds_read_b32 v12, v30 offset:988
	s_waitcnt lgkmcnt(0)
	v_mul_f32_e32 v9, 0x42800000, v9
	v_mul_f32_e32 v10, 0x42800000, v10
	v_med3_f32 v13, v9, s10, v46
	v_med3_f32 v10, v10, s10, v46
	v_mov_b32_e32 v9, v3
	v_cvt_pk_fp8_f32 v9, v13, v10
	v_mul_f32_e32 v11, 0x42800000, v11
	v_mul_f32_e32 v12, 0x42800000, v12
	v_med3_f32 v10, v11, s10, v46
	v_med3_f32 v11, v12, s10, v46
	v_cvt_pk_fp8_f32 v9, v10, v11 op_sel:[0,0,1]
	v_or_b32_e32 v10, s12, v28
	v_ashrrev_i32_e32 v11, 31, v10
	v_lshlrev_b64 v[10:11], 10, v[10:11]
	v_lshl_add_u64 v[10:11], v[6:7], 0, v[10:11]
	flat_store_dwordx2 v[10:11], v[8:9]
	ds_read_b32 v8, v30 offset:96
	ds_read_b32 v9, v30 offset:228
	ds_read_b32 v10, v30 offset:360
	ds_read_b32 v11, v30 offset:492
	s_waitcnt lgkmcnt(0)
	v_mul_f32_e32 v8, 0x42800000, v8
	v_mul_f32_e32 v9, 0x42800000, v9
	v_med3_f32 v12, v8, s10, v46
	v_med3_f32 v9, v9, s10, v46
	v_mov_b32_e32 v8, v3
	v_cvt_pk_fp8_f32 v8, v12, v9
	v_mul_f32_e32 v10, 0x42800000, v10
	v_mul_f32_e32 v11, 0x42800000, v11
	v_med3_f32 v9, v10, s10, v46
	v_med3_f32 v10, v11, s10, v46
	v_cvt_pk_fp8_f32 v8, v9, v10 op_sel:[0,0,1]
	ds_read_b32 v9, v30 offset:624
	ds_read_b32 v10, v30 offset:756
	ds_read_b32 v11, v30 offset:888
	ds_read_b32 v12, v30 offset:1020
	s_waitcnt lgkmcnt(0)
	v_mul_f32_e32 v9, 0x42800000, v9
	v_mul_f32_e32 v10, 0x42800000, v10
	v_med3_f32 v13, v9, s10, v46
	v_med3_f32 v10, v10, s10, v46
	v_mov_b32_e32 v9, v3
	v_cvt_pk_fp8_f32 v9, v13, v10
	v_mul_f32_e32 v11, 0x42800000, v11
	v_mul_f32_e32 v12, 0x42800000, v12
	v_med3_f32 v10, v11, s10, v46
	v_med3_f32 v11, v12, s10, v46
	v_cvt_pk_fp8_f32 v9, v10, v11 op_sel:[0,0,1]
	v_or_b32_e32 v10, s12, v29
	v_ashrrev_i32_e32 v11, 31, v10
	v_lshlrev_b64 v[10:11], 10, v[10:11]
	v_lshl_add_u64 v[6:7], v[6:7], 0, v[10:11]
	flat_store_dwordx2 v[6:7], v[8:9]
	s_waitcnt lgkmcnt(0)
	s_branch .LBB0_1443

.LBB0_2166:
	s_or_b64 exec, exec, s[12:13]
	s_waitcnt lgkmcnt(0)
	s_barrier
	s_load_dwordx8 s[16:23], s[84:85], 0xd8
	s_load_dwordx4 s[8:11], s[84:85], 0xf8
	s_load_dwordx2 s[0:1], s[84:85], 0x108
	v_mov_b32_e32 v45, v0
	v_mov_b32_e32 v35, 0
	v_and_b32_e32 v74, 63, v45
	s_waitcnt lgkmcnt(0)
	s_mov_b32 s6, s0
	s_mov_b32 s0, s10
	s_add_u32 s24, s6, 0x3e00000
	s_addc_u32 s25, s1, 0
	v_lshlrev_b32_e32 v34, 4, v74
	v_lshl_add_u64 v[2:3], s[22:23], 0, v[34:35]
	s_mov_b64 s[4:5], 0x5000
	s_movk_i32 s0, 0x5000
	s_add_u32 s22, s6, 0x3900000
	v_lshl_add_u64 v[26:27], v[2:3], 0, s[4:5]
	v_add_co_u32_e32 v2, vcc, s0, v2
	s_addc_u32 s23, s1, 0
	v_lshl_add_u64 v[6:7], s[8:9], 0, v[34:35]
	v_addc_co_u32_e32 v3, vcc, 0, v3, vcc
	s_add_u32 s14, s6, 0xa100000
	s_mov_b32 s7, s1
	v_lshl_add_u64 v[30:31], v[6:7], 0, s[4:5]
	v_add_co_u32_e32 v6, vcc, s0, v6
	s_addc_u32 s15, s1, 0
	v_readlane_b32 s0, v253, 36
	v_readlane_b32 s1, v253, 37
	s_add_u32 s0, s14, s0
	s_addc_u32 s1, s15, s1
	v_readlane_b32 s4, v253, 38
	v_readlane_b32 s5, v253, 39
	s_add_u32 s4, s14, s4
	s_addc_u32 s5, s15, s5
	v_lshlrev_b32_e32 v34, 3, v74
	v_addc_co_u32_e32 v7, vcc, 0, v7, vcc
	v_lshl_add_u64 v[42:43], s[0:1], 0, v[34:35]
	v_lshl_add_u64 v[46:47], s[4:5], 0, v[34:35]
	global_load_dwordx4 v[2:5], v[2:3], off nt
	s_nop 0
	global_load_dwordx4 v[6:9], v[6:7], off nt
	s_nop 0
	global_load_dwordx4 v[10:13], v[26:27], off offset:1024
	global_load_dwordx4 v[14:17], v[30:31], off offset:1024
	global_load_dwordx4 v[18:21], v[26:27], off offset:2048
	global_load_dwordx4 v[22:25], v[30:31], off offset:2048
	s_nop 0
	global_load_dwordx4 v[26:29], v[26:27], off offset:3072
	s_nop 0
	global_load_dwordx4 v[30:33], v[30:31], off offset:3072
	v_cmp_gt_u32_e64 s[12:13], 16, v74
	flat_load_dwordx2 v[62:63], v[42:43]
	flat_load_dwordx2 v[36:37], v[46:47]
	flat_load_dwordx2 v[64:65], v[42:43] offset:512
	flat_load_dwordx2 v[38:39], v[46:47] offset:512
	flat_load_dwordx2 v[60:61], v[42:43] offset:1024
	flat_load_dwordx2 v[40:41], v[46:47] offset:1024
	flat_load_dwordx2 v[58:59], v[42:43] offset:1536
	s_nop 0
	flat_load_dwordx2 v[42:43], v[46:47] offset:1536
	v_mov_b32_e32 v75, -1
	v_lshlrev_b32_e32 v44, 11, v74
	v_mov_b32_e32 v82, v35
	v_mov_b32_e32 v81, -1
	s_and_saveexec_b64 s[26:27], s[12:13]
	s_cbranch_execz .LBB0_2168
	v_readlane_b32 s0, v253, 34
	v_readlane_b32 s1, v253, 35
	s_mov_b32 s4, s0
	s_ashr_i32 s0, s0, 11
	s_ashr_i32 s1, s0, 31
	s_lshl_b64 s[0:1], s[0:1], 15
	s_and_b32 s4, s4, 0x7ff
	s_or_b32 s0, s0, s4
	s_ashr_i32 s4, s68, 11
	s_ashr_i32 s5, s4, 31
	s_lshl_b64 s[4:5], s[4:5], 15
	s_and_b32 s8, s68, 0x7ff
	s_or_b32 s4, s4, s8
	v_or_b32_e32 v46, s4, v44
	v_mov_b32_e32 v47, s5
	v_lshl_add_u64 v[48:49], v[46:47], 1, s[24:25]
	v_lshl_add_u64 v[46:47], v[46:47], 2, s[22:23]
	flat_load_sshort v81, v[48:49]
	flat_load_dword v82, v[46:47]
	v_or_b32_e32 v46, s0, v44
	v_mov_b32_e32 v47, s1
	v_lshl_add_u64 v[48:49], v[46:47], 1, s[24:25]
	v_lshl_add_u64 v[46:47], v[46:47], 2, s[22:23]
	flat_load_sshort v75, v[48:49]
	flat_load_dword v35, v[46:47]

.LBB0_2183:
	s_mul_hi_i32 s0, s21, 0x2aaaaaab
	s_lshr_b32 s1, s0, 31
	s_ashr_i32 s0, s0, 8
	s_add_i32 s12, s0, s1
	s_mul_i32 s0, s12, 0xfffffa00
	s_add_i32 s24, s21, s0
	s_lshr_b32 s0, s24, 22
	s_and_b32 s0, s0, 0x1ff
	s_add_i32 s25, s24, s0
	s_and_b32 s0, s25, 0xfe00
	s_sub_i32 s0, s24, s0
	s_sext_i32_i16 s1, s0
	s_bfe_u32 s1, s1, 0x5001a
	s_add_i32 s1, s0, s1
	s_sext_i32_i16 s10, s1
	s_and_b32 s1, s1, 0xffe0
	s_lshl_b32 s23, s10, 1
	s_sub_i32 s0, s0, s1
	s_andn2_b32 s23, s23, 63
	s_sext_i32_i16 s22, s0
	s_lshl_b32 s10, s22, 5
	v_or_b32_e32 v20, s23, v26
	s_mov_b64 s[14:15], -1
	s_cmpk_gt_i32 s24, 0x3ff
	v_ashrrev_i32_e32 v21, 31, v20
	v_or_b32_e32 v18, 8, v20
	v_or_b32_e32 v16, 16, v20
	v_or_b32_e32 v14, 24, v20
	v_or_b32_e32 v12, 32, v20
	v_or_b32_e32 v10, 40, v20
	v_or_b32_e32 v8, 48, v20
	v_or_b32_e32 v6, 56, v20
	s_cbranch_scc0 .LBB0_2185
	s_ashr_i32 s13, s12, 31
	s_lshl_b64 s[0:1], s[12:13], 20
	s_lshl_b64 s[14:15], s[12:13], 22
	s_add_u32 s13, s8, s14
	s_addc_u32 s14, s9, s15
	s_add_u32 s15, s6, s0
	s_addc_u32 s26, s7, s1
	s_ashr_i32 s11, s10, 31
	s_lshl_b64 s[0:1], s[10:11], 2
	s_add_u32 s0, s13, s0
	s_addc_u32 s1, s14, s1
	v_lshl_add_u64 v[72:73], s[0:1], 0, v[2:3]
	v_lshlrev_b64 v[22:23], 12, v[20:21]
	v_lshl_add_u64 v[22:23], v[72:73], 0, v[22:23]
	v_ashrrev_i32_e32 v19, 31, v18
	global_load_dwordx4 v[22:25], v[22:23], off nt
	v_lshlrev_b64 v[48:49], 12, v[18:19]
	v_lshl_add_u64 v[48:49], v[72:73], 0, v[48:49]
	v_ashrrev_i32_e32 v17, 31, v16
	global_load_dwordx4 v[48:51], v[48:49], off nt
	v_lshlrev_b64 v[52:53], 12, v[16:17]
	v_lshl_add_u64 v[52:53], v[72:73], 0, v[52:53]
	v_ashrrev_i32_e32 v15, 31, v14
	global_load_dwordx4 v[52:55], v[52:53], off nt
	v_lshlrev_b64 v[56:57], 12, v[14:15]
	v_lshl_add_u64 v[56:57], v[72:73], 0, v[56:57]
	v_ashrrev_i32_e32 v13, 31, v12
	global_load_dwordx4 v[56:59], v[56:57], off nt
	v_lshlrev_b64 v[60:61], 12, v[12:13]
	v_lshl_add_u64 v[60:61], v[72:73], 0, v[60:61]
	v_ashrrev_i32_e32 v11, 31, v10
	global_load_dwordx4 v[60:63], v[60:61], off nt
	v_lshlrev_b64 v[64:65], 12, v[10:11]
	v_lshl_add_u64 v[64:65], v[72:73], 0, v[64:65]
	v_ashrrev_i32_e32 v9, 31, v8
	global_load_dwordx4 v[64:67], v[64:65], off nt
	v_lshlrev_b64 v[68:69], 12, v[8:9]
	v_lshl_add_u64 v[68:69], v[72:73], 0, v[68:69]
	v_ashrrev_i32_e32 v7, 31, v6
	global_load_dwordx4 v[68:71], v[68:69], off nt
	v_lshlrev_b64 v[74:75], 12, v[6:7]
	v_lshl_add_u64 v[72:73], v[72:73], 0, v[74:75]
	global_load_dwordx4 v[72:75], v[72:73], off nt
	s_ashr_i32 s1, s23, 31
	s_add_u32 s0, s15, s23
	s_addc_u32 s1, s26, s1
	s_waitcnt vmcnt(0)
	ds_write2_b32 v31, v22, v23 offset1:1
	ds_write2_b32 v31, v24, v25 offset0:2 offset1:3
	s_waitcnt vmcnt(6)
	ds_write2_b32 v32, v48, v49 offset1:1
	ds_write2_b32 v33, v50, v51 offset1:1
	s_waitcnt vmcnt(5)
	ds_write2_b32 v34, v52, v53 offset1:1
	ds_write2_b32 v35, v54, v55 offset1:1
	s_waitcnt vmcnt(4)
	ds_write2_b32 v36, v56, v57 offset1:1
	ds_write2_b32 v37, v58, v59 offset1:1
	s_waitcnt vmcnt(3)
	ds_write2_b32 v38, v60, v61 offset1:1
	ds_write2_b32 v39, v62, v63 offset1:1
	s_waitcnt vmcnt(2)
	ds_write2_b32 v40, v64, v65 offset1:1
	ds_write2_b32 v41, v66, v67 offset1:1
	s_waitcnt vmcnt(1)
	ds_write2_b32 v42, v68, v69 offset1:1
	ds_write2_b32 v43, v70, v71 offset1:1
	s_waitcnt vmcnt(0)
	ds_write2_b32 v44, v72, v73 offset1:1
	ds_write2_b32 v45, v74, v75 offset1:1
	s_waitcnt lgkmcnt(0)
	ds_read_b32 v7, v30
	ds_read_b32 v9, v30 offset:132
	ds_read_b32 v11, v30 offset:264
	ds_read_b32 v13, v30 offset:396
	v_mov_b32_e32 v24, v3
	s_waitcnt lgkmcnt(0)
	v_mul_f32_e32 v7, 0x43000000, v7
	s_waitcnt lgkmcnt(2)
	v_mul_f32_e32 v9, 0x43000000, v9
	v_med3_f32 v7, v7, s20, v46
	v_med3_f32 v9, v9, s20, v46
	v_cvt_pk_fp8_f32 v24, v7, v9
	s_waitcnt lgkmcnt(1)
	v_mul_f32_e32 v11, 0x43000000, v11
	s_waitcnt lgkmcnt(0)
	v_mul_f32_e32 v13, 0x43000000, v13
	v_med3_f32 v7, v11, s20, v46
	v_med3_f32 v9, v13, s20, v46
	v_cvt_pk_fp8_f32 v24, v7, v9 op_sel:[0,0,1]
	ds_read_b32 v7, v30 offset:528
	ds_read_b32 v9, v30 offset:660
	ds_read_b32 v11, v30 offset:792
	ds_read_b32 v13, v30 offset:924
	v_mov_b32_e32 v25, v3
	s_waitcnt lgkmcnt(3)
	v_mul_f32_e32 v7, 0x43000000, v7
	s_waitcnt lgkmcnt(2)
	v_mul_f32_e32 v9, 0x43000000, v9
	v_med3_f32 v7, v7, s20, v46
	v_med3_f32 v9, v9, s20, v46
	v_cvt_pk_fp8_f32 v25, v7, v9
	s_waitcnt lgkmcnt(1)
	v_mul_f32_e32 v11, 0x43000000, v11
	s_waitcnt lgkmcnt(0)
	v_mul_f32_e32 v13, 0x43000000, v13
	v_med3_f32 v7, v11, s20, v46
	v_med3_f32 v9, v13, s20, v46
	v_cvt_pk_fp8_f32 v25, v7, v9 op_sel:[0,0,1]
	v_or_b32_e32 v48, s10, v26
	v_ashrrev_i32_e32 v49, 31, v48
	v_lshl_add_u64 v[22:23], s[0:1], 0, v[4:5]
	v_lshlrev_b64 v[48:49], 10, v[48:49]
	v_lshl_add_u64 v[48:49], v[22:23], 0, v[48:49]
	flat_store_dwordx2 v[48:49], v[24:25]
	ds_read_b32 v7, v30 offset:32
	ds_read_b32 v9, v30 offset:164
	ds_read_b32 v11, v30 offset:296
	ds_read_b32 v13, v30 offset:428
	v_mov_b32_e32 v24, v3
	s_waitcnt lgkmcnt(0)
	v_mul_f32_e32 v7, 0x43000000, v7
	v_mul_f32_e32 v9, 0x43000000, v9
	v_med3_f32 v7, v7, s20, v46
	v_med3_f32 v9, v9, s20, v46
	v_cvt_pk_fp8_f32 v24, v7, v9
	v_mul_f32_e32 v11, 0x43000000, v11
	v_mul_f32_e32 v13, 0x43000000, v13
	v_med3_f32 v7, v11, s20, v46
	v_med3_f32 v9, v13, s20, v46
	v_cvt_pk_fp8_f32 v24, v7, v9 op_sel:[0,0,1]
	ds_read_b32 v7, v30 offset:560
	ds_read_b32 v9, v30 offset:692
	ds_read_b32 v11, v30 offset:824
	ds_read_b32 v13, v30 offset:956
	v_mov_b32_e32 v25, v3
	s_waitcnt lgkmcnt(0)
	v_mul_f32_e32 v7, 0x43000000, v7
	v_mul_f32_e32 v9, 0x43000000, v9
	v_med3_f32 v7, v7, s20, v46
	v_med3_f32 v9, v9, s20, v46
	v_cvt_pk_fp8_f32 v25, v7, v9
	v_mul_f32_e32 v11, 0x43000000, v11
	v_mul_f32_e32 v13, 0x43000000, v13
	v_med3_f32 v7, v11, s20, v46
	v_med3_f32 v9, v13, s20, v46
	v_cvt_pk_fp8_f32 v25, v7, v9 op_sel:[0,0,1]
	v_or_b32_e32 v48, s10, v27
	v_ashrrev_i32_e32 v49, 31, v48
	v_lshlrev_b64 v[48:49], 10, v[48:49]
	v_lshl_add_u64 v[48:49], v[22:23], 0, v[48:49]
	flat_store_dwordx2 v[48:49], v[24:25]
	ds_read_b32 v7, v30 offset:64
	ds_read_b32 v9, v30 offset:196
	ds_read_b32 v11, v30 offset:328
	ds_read_b32 v13, v30 offset:460
	v_mov_b32_e32 v24, v3
	s_waitcnt lgkmcnt(0)
	v_mul_f32_e32 v7, 0x43000000, v7
	v_mul_f32_e32 v9, 0x43000000, v9
	v_med3_f32 v7, v7, s20, v46
	v_med3_f32 v9, v9, s20, v46
	v_cvt_pk_fp8_f32 v24, v7, v9
	v_mul_f32_e32 v11, 0x43000000, v11
	v_mul_f32_e32 v13, 0x43000000, v13
	v_med3_f32 v7, v11, s20, v46
	v_med3_f32 v9, v13, s20, v46
	v_cvt_pk_fp8_f32 v24, v7, v9 op_sel:[0,0,1]
	ds_read_b32 v7, v30 offset:592
	ds_read_b32 v9, v30 offset:724
	ds_read_b32 v11, v30 offset:856
	ds_read_b32 v13, v30 offset:988
	v_mov_b32_e32 v25, v3
	s_waitcnt lgkmcnt(0)
	v_mul_f32_e32 v7, 0x43000000, v7
	v_mul_f32_e32 v9, 0x43000000, v9
	v_med3_f32 v7, v7, s20, v46
	v_med3_f32 v9, v9, s20, v46
	v_cvt_pk_fp8_f32 v25, v7, v9
	v_mul_f32_e32 v11, 0x43000000, v11
	v_mul_f32_e32 v13, 0x43000000, v13
	v_med3_f32 v7, v11, s20, v46
	v_med3_f32 v9, v13, s20, v46
	v_cvt_pk_fp8_f32 v25, v7, v9 op_sel:[0,0,1]
	v_or_b32_e32 v48, s10, v28
	v_ashrrev_i32_e32 v49, 31, v48
	v_lshlrev_b64 v[48:49], 10, v[48:49]
	v_lshl_add_u64 v[48:49], v[22:23], 0, v[48:49]
	flat_store_dwordx2 v[48:49], v[24:25]
	ds_read_b32 v7, v30 offset:96
	ds_read_b32 v9, v30 offset:228
	ds_read_b32 v11, v30 offset:360
	ds_read_b32 v13, v30 offset:492
	v_mov_b32_e32 v24, v3
	s_waitcnt lgkmcnt(0)
	v_mul_f32_e32 v7, 0x43000000, v7
	v_mul_f32_e32 v9, 0x43000000, v9
	v_med3_f32 v7, v7, s20, v46
	v_med3_f32 v9, v9, s20, v46
	v_cvt_pk_fp8_f32 v24, v7, v9
	v_mul_f32_e32 v11, 0x43000000, v11
	v_mul_f32_e32 v13, 0x43000000, v13
	v_med3_f32 v7, v11, s20, v46
	v_med3_f32 v9, v13, s20, v46
	v_cvt_pk_fp8_f32 v24, v7, v9 op_sel:[0,0,1]
	ds_read_b32 v7, v30 offset:624
	ds_read_b32 v9, v30 offset:756
	ds_read_b32 v11, v30 offset:888
	ds_read_b32 v13, v30 offset:1020
	v_mov_b32_e32 v25, v3
	s_waitcnt lgkmcnt(0)
	v_mul_f32_e32 v7, 0x43000000, v7
	v_mul_f32_e32 v9, 0x43000000, v9
	v_med3_f32 v7, v7, s20, v46
	v_med3_f32 v9, v9, s20, v46
	v_cvt_pk_fp8_f32 v25, v7, v9
	v_mul_f32_e32 v11, 0x43000000, v11
	v_mul_f32_e32 v13, 0x43000000, v13
	v_med3_f32 v7, v11, s20, v46
	v_med3_f32 v9, v13, s20, v46
	v_cvt_pk_fp8_f32 v25, v7, v9 op_sel:[0,0,1]
	v_or_b32_e32 v48, s10, v29
	v_ashrrev_i32_e32 v49, 31, v48
	v_lshlrev_b64 v[48:49], 10, v[48:49]
	v_lshl_add_u64 v[22:23], v[22:23], 0, v[48:49]
	flat_store_dwordx2 v[22:23], v[24:25]
	s_waitcnt lgkmcnt(0)
	s_cbranch_execnz .LBB0_2182
	s_branch .LBB0_2186

.LBB0_2186:
	s_sext_i32_i16 s0, s25
	s_lshr_b32 s0, s0, 9
	s_addk_i32 s24, 0x1ff
	s_cmpk_lt_u32 s24, 0x3ff
	s_cselect_b32 s11, s17, s19
	s_cselect_b32 s15, s16, s18
	s_ashr_i32 s13, s12, 31
	s_sext_i32_i16 s14, s0
	s_lshl_b64 s[0:1], s[12:13], 22
	s_add_u32 s15, s15, s0
	s_addc_u32 s24, s11, s1
	s_lshl_b64 s[0:1], s[12:13], 21
	s_add_u32 s12, s4, s0
	s_addc_u32 s13, s5, s1
	s_ashr_i32 s11, s10, 31
	s_lshl_b64 s[0:1], s[10:11], 2
	s_add_u32 s0, s15, s0
	s_addc_u32 s1, s24, s1
	v_lshl_add_u64 v[22:23], s[0:1], 0, v[2:3]
	s_mov_b64 s[0:1], 0xc000000
	v_lshl_add_u64 v[24:25], v[22:23], 0, s[0:1]
	v_lshlrev_b64 v[20:21], 12, v[20:21]
	v_lshl_add_u64 v[20:21], v[24:25], 0, v[20:21]
	v_ashrrev_i32_e32 v19, 31, v18
	global_load_dwordx4 v[20:23], v[20:21], off nt
	v_lshlrev_b64 v[18:19], 12, v[18:19]
	v_lshl_add_u64 v[18:19], v[24:25], 0, v[18:19]
	v_ashrrev_i32_e32 v17, 31, v16
	global_load_dwordx4 v[48:51], v[18:19], off nt
	v_lshlrev_b64 v[16:17], 12, v[16:17]
	v_lshl_add_u64 v[16:17], v[24:25], 0, v[16:17]
	v_ashrrev_i32_e32 v15, 31, v14
	global_load_dwordx4 v[16:19], v[16:17], off nt
	v_lshlrev_b64 v[14:15], 12, v[14:15]
	v_lshl_add_u64 v[14:15], v[24:25], 0, v[14:15]
	v_ashrrev_i32_e32 v13, 31, v12
	global_load_dwordx4 v[52:55], v[14:15], off nt
	v_lshlrev_b64 v[12:13], 12, v[12:13]
	v_lshl_add_u64 v[12:13], v[24:25], 0, v[12:13]
	v_ashrrev_i32_e32 v11, 31, v10
	global_load_dwordx4 v[12:15], v[12:13], off nt
	v_lshlrev_b64 v[10:11], 12, v[10:11]
	v_lshl_add_u64 v[10:11], v[24:25], 0, v[10:11]
	v_ashrrev_i32_e32 v9, 31, v8
	global_load_dwordx4 v[56:59], v[10:11], off nt
	v_lshlrev_b64 v[8:9], 12, v[8:9]
	v_lshl_add_u64 v[8:9], v[24:25], 0, v[8:9]
	v_ashrrev_i32_e32 v7, 31, v6
	global_load_dwordx4 v[8:11], v[8:9], off nt
	v_lshlrev_b64 v[6:7], 12, v[6:7]
	v_lshl_add_u64 v[6:7], v[24:25], 0, v[6:7]
	global_load_dwordx4 v[60:63], v[6:7], off nt
	s_lshl_b32 s1, s14, 7
	s_ashr_i32 s0, s23, 31
	s_add_u32 s12, s12, s23
	s_addc_u32 s13, s13, s0
	s_lshl_b32 s0, s22, 6
	s_and_b32 s0, s0, 0xffffff00
	s_add_i32 s0, s0, s1
	s_and_b32 s1, s10, 0x60
	s_or_b32 s10, s0, s1
	v_lshl_add_u64 v[6:7], s[12:13], 0, v[4:5]
	s_waitcnt vmcnt(0)
	ds_write2_b32 v31, v20, v21 offset1:1
	ds_write2_b32 v31, v22, v23 offset0:2 offset1:3
	ds_write2_b32 v32, v48, v49 offset1:1
	ds_write2_b32 v33, v50, v51 offset1:1
	ds_write2_b32 v34, v16, v17 offset1:1
	ds_write2_b32 v35, v18, v19 offset1:1
	ds_write2_b32 v36, v52, v53 offset1:1
	ds_write2_b32 v37, v54, v55 offset1:1
	ds_write2_b32 v38, v12, v13 offset1:1
	ds_write2_b32 v39, v14, v15 offset1:1
	ds_write2_b32 v40, v56, v57 offset1:1
	ds_write2_b32 v41, v58, v59 offset1:1
	ds_write2_b32 v42, v8, v9 offset1:1
	ds_write2_b32 v43, v10, v11 offset1:1
	ds_write2_b32 v44, v60, v61 offset1:1
	ds_write2_b32 v45, v62, v63 offset1:1
	s_waitcnt lgkmcnt(0)
	ds_read_b32 v8, v30
	ds_read_b32 v9, v30 offset:132
	ds_read_b32 v10, v30 offset:264
	ds_read_b32 v11, v30 offset:396
	s_waitcnt lgkmcnt(0)
	v_mul_f32_e32 v8, 0x42800000, v8
	v_mul_f32_e32 v9, 0x42800000, v9
	v_med3_f32 v12, v8, s20, v46
	v_med3_f32 v9, v9, s20, v46
	v_mov_b32_e32 v8, v3
	v_cvt_pk_fp8_f32 v8, v12, v9
	v_mul_f32_e32 v10, 0x42800000, v10
	v_mul_f32_e32 v11, 0x42800000, v11
	v_med3_f32 v9, v10, s20, v46
	v_med3_f32 v10, v11, s20, v46
	v_cvt_pk_fp8_f32 v8, v9, v10 op_sel:[0,0,1]
	ds_read_b32 v9, v30 offset:528
	ds_read_b32 v10, v30 offset:660
	ds_read_b32 v11, v30 offset:792
	ds_read_b32 v12, v30 offset:924
	s_waitcnt lgkmcnt(3)
	v_mul_f32_e32 v9, 0x42800000, v9
	s_waitcnt lgkmcnt(2)
	v_mul_f32_e32 v10, 0x42800000, v10
	v_med3_f32 v13, v9, s20, v46
	v_med3_f32 v10, v10, s20, v46
	v_mov_b32_e32 v9, v3
	v_cvt_pk_fp8_f32 v9, v13, v10
	s_waitcnt lgkmcnt(1)
	v_mul_f32_e32 v11, 0x42800000, v11
	s_waitcnt lgkmcnt(0)
	v_mul_f32_e32 v12, 0x42800000, v12
	v_med3_f32 v10, v11, s20, v46
	v_med3_f32 v11, v12, s20, v46
	v_cvt_pk_fp8_f32 v9, v10, v11 op_sel:[0,0,1]
	v_or_b32_e32 v10, s10, v26
	v_ashrrev_i32_e32 v11, 31, v10
	v_lshlrev_b64 v[10:11], 10, v[10:11]
	v_lshl_add_u64 v[10:11], v[6:7], 0, v[10:11]
	flat_store_dwordx2 v[10:11], v[8:9]
	ds_read_b32 v8, v30 offset:32
	ds_read_b32 v9, v30 offset:164
	ds_read_b32 v10, v30 offset:296
	ds_read_b32 v11, v30 offset:428
	s_waitcnt lgkmcnt(0)
	v_mul_f32_e32 v8, 0x42800000, v8
	v_mul_f32_e32 v9, 0x42800000, v9
	v_med3_f32 v12, v8, s20, v46
	v_med3_f32 v9, v9, s20, v46
	v_mov_b32_e32 v8, v3
	v_cvt_pk_fp8_f32 v8, v12, v9
	v_mul_f32_e32 v10, 0x42800000, v10
	v_mul_f32_e32 v11, 0x42800000, v11
	v_med3_f32 v9, v10, s20, v46
	v_med3_f32 v10, v11, s20, v46
	v_cvt_pk_fp8_f32 v8, v9, v10 op_sel:[0,0,1]
	ds_read_b32 v9, v30 offset:560
	ds_read_b32 v10, v30 offset:692
	ds_read_b32 v11, v30 offset:824
	ds_read_b32 v12, v30 offset:956
	s_waitcnt lgkmcnt(0)
	v_mul_f32_e32 v9, 0x42800000, v9
	v_mul_f32_e32 v10, 0x42800000, v10
	v_med3_f32 v13, v9, s20, v46
	v_med3_f32 v10, v10, s20, v46
	v_mov_b32_e32 v9, v3
	v_cvt_pk_fp8_f32 v9, v13, v10
	v_mul_f32_e32 v11, 0x42800000, v11
	v_mul_f32_e32 v12, 0x42800000, v12
	v_med3_f32 v10, v11, s20, v46
	v_med3_f32 v11, v12, s20, v46
	v_cvt_pk_fp8_f32 v9, v10, v11 op_sel:[0,0,1]
	v_or_b32_e32 v10, s10, v27
	v_ashrrev_i32_e32 v11, 31, v10
	v_lshlrev_b64 v[10:11], 10, v[10:11]
	v_lshl_add_u64 v[10:11], v[6:7], 0, v[10:11]
	flat_store_dwordx2 v[10:11], v[8:9]
	ds_read_b32 v8, v30 offset:64
	ds_read_b32 v9, v30 offset:196
	ds_read_b32 v10, v30 offset:328
	ds_read_b32 v11, v30 offset:460
	s_waitcnt lgkmcnt(0)
	v_mul_f32_e32 v8, 0x42800000, v8
	v_mul_f32_e32 v9, 0x42800000, v9
	v_med3_f32 v12, v8, s20, v46
	v_med3_f32 v9, v9, s20, v46
	v_mov_b32_e32 v8, v3
	v_cvt_pk_fp8_f32 v8, v12, v9
	v_mul_f32_e32 v10, 0x42800000, v10
	v_mul_f32_e32 v11, 0x42800000, v11
	v_med3_f32 v9, v10, s20, v46
	v_med3_f32 v10, v11, s20, v46
	v_cvt_pk_fp8_f32 v8, v9, v10 op_sel:[0,0,1]
	ds_read_b32 v9, v30 offset:592
	ds_read_b32 v10, v30 offset:724
	ds_read_b32 v11, v30 offset:856
	ds_read_b32 v12, v30 offset:988
	s_waitcnt lgkmcnt(0)
	v_mul_f32_e32 v9, 0x42800000, v9
	v_mul_f32_e32 v10, 0x42800000, v10
	v_med3_f32 v13, v9, s20, v46
	v_med3_f32 v10, v10, s20, v46
	v_mov_b32_e32 v9, v3
	v_cvt_pk_fp8_f32 v9, v13, v10
	v_mul_f32_e32 v11, 0x42800000, v11
	v_mul_f32_e32 v12, 0x42800000, v12
	v_med3_f32 v10, v11, s20, v46
	v_med3_f32 v11, v12, s20, v46
	v_cvt_pk_fp8_f32 v9, v10, v11 op_sel:[0,0,1]
	v_or_b32_e32 v10, s10, v28
	v_ashrrev_i32_e32 v11, 31, v10
	v_lshlrev_b64 v[10:11], 10, v[10:11]
	v_lshl_add_u64 v[10:11], v[6:7], 0, v[10:11]
	flat_store_dwordx2 v[10:11], v[8:9]
	ds_read_b32 v8, v30 offset:96
	ds_read_b32 v9, v30 offset:228
	ds_read_b32 v10, v30 offset:360
	ds_read_b32 v11, v30 offset:492
	s_waitcnt lgkmcnt(0)
	v_mul_f32_e32 v8, 0x42800000, v8
	v_mul_f32_e32 v9, 0x42800000, v9
	v_med3_f32 v12, v8, s20, v46
	v_med3_f32 v9, v9, s20, v46
	v_mov_b32_e32 v8, v3
	v_cvt_pk_fp8_f32 v8, v12, v9
	v_mul_f32_e32 v10, 0x42800000, v10
	v_mul_f32_e32 v11, 0x42800000, v11
	v_med3_f32 v9, v10, s20, v46
	v_med3_f32 v10, v11, s20, v46
	v_cvt_pk_fp8_f32 v8, v9, v10 op_sel:[0,0,1]
	ds_read_b32 v9, v30 offset:624
	ds_read_b32 v10, v30 offset:756
	ds_read_b32 v11, v30 offset:888
	ds_read_b32 v12, v30 offset:1020
	s_waitcnt lgkmcnt(0)
	v_mul_f32_e32 v9, 0x42800000, v9
	v_mul_f32_e32 v10, 0x42800000, v10
	v_med3_f32 v13, v9, s20, v46
	v_med3_f32 v10, v10, s20, v46
	v_mov_b32_e32 v9, v3
	v_cvt_pk_fp8_f32 v9, v13, v10
	v_mul_f32_e32 v11, 0x42800000, v11
	v_mul_f32_e32 v12, 0x42800000, v12
	v_med3_f32 v10, v11, s20, v46
	v_med3_f32 v11, v12, s20, v46
	v_cvt_pk_fp8_f32 v9, v10, v11 op_sel:[0,0,1]
	v_or_b32_e32 v10, s10, v29
	v_ashrrev_i32_e32 v11, 31, v10
	v_lshlrev_b64 v[10:11], 10, v[10:11]
	v_lshl_add_u64 v[6:7], v[6:7], 0, v[10:11]
	flat_store_dwordx2 v[6:7], v[8:9]
	s_waitcnt lgkmcnt(0)
	s_branch .LBB0_2182
